# v26 + LRU loop: next unit's PROJ lines touched into L2 via LDS-DMA dummy loads; loop-head store drain removed
# baseline (speedup 1.0000x reference)
; #define LAS __attribute__((address_space(3)))
; template <bool FINAL, bool SMP>
; __device__ __forceinline__ void lru_unit(const Args& args, int l, int p, int h, LAS unsigned char* lds, int wave, int lane) {
;     ...
;     const int b = SMP ? (p - 64) * 8 + wave : (p >> 5);
;     const int t0 = SMP ? 0 : ((p & 31) * 256 + 32 * wave);
;     const int R0 = p * 256 + 32 * wave;
;     LAS float* WA = (LAS float*)lds; LAS float* WB = WA + 8 * 64; LAS float* HIN = WB + 8 * 64;
;     u32x4 xr[2][2][4];
;     f32x4 cwv[2][4][2], cbv[2][2];
;     {
;         const float* cw = args.in[I_LCW] + (size_t)l * 4 * LW; const float* cb = args.in[I_LCB] + (size_t)l * LW;
; #pragma unroll
;         for (int ks = 0; ks < 2; ++ks) {
;             const int c0 = h * 64 + 32 * ks + 8 * g;
; #pragma unroll
;             for (int mt = 0; mt < 2; ++mt)
; #pragma unroll
;                 for (int k = 0; k < 4; ++k) { const int rr = R0 + 16 * mt + r16 + k - 3; const bf16_t* src = PROJ + (size_t)(rr < 0 ? 0 : rr) * INC + C_LX + c0;
;                     if (SMP && mt == 0 && k < 3) { const int ts = r16 + k - 3; const bf16_t* alt = (const bf16_t*)(ws + WS_SLCB) + ((size_t)(l * DBATCH + b) * 3 + (ts < 0 ? 3 + ts : 0)) * LW + c0; src = ts < 0 ? alt : src; }
;                     xr[ks][mt][k] = *(const u32x4*)src; }
; __global__ void __launch_bounds__(512, 2) mk_fwd(Args args) {
;     ...
;             for (int u = vcu; u < 64 * LHEADS; u += G) lru_unit<true, false>(args, l, u >> 4, u & 15, lds, wave, lane);
.LBB0_610:
	s_ashr_i32 s25, s21, 4
	v_mov_b32_e32 v106, v1
	s_lshl_b32 s24, s25, 8
	v_readlane_b32 s26, v251, 15
	s_and_b32 s0, s21, 15
	s_add_i32 s24, s24, s26
	s_lshl_b32 s98, s0, 7
	s_add_u32 s98, s10, s98
	s_addc_u32 s99, s11, 0
	s_add_u32 s98, s98, 0x6000000
	s_addc_u32 s99, s99, 0
	v_add_u32_e32 v166, s24, v106
	v_add_u32_e32 v166, -3, v166
	v_max_i32_e32 v166, 0, v166
	v_mul_u32_u24_e32 v166, 0x6000, v166
	v_and_b32_e32 v167, 31, v106
	v_add_u32_e32 v167, s24, v167
	v_mul_u32_u24_e32 v167, 0x6000, v167
	v_and_b32_e32 v125, 15, v106
	v_ashrrev_i32_e32 v124, 4, v106
	s_lshl_b32 s23, s0, 6
	v_lshlrev_b32_e32 v108, 3, v124
	v_or_b32_e32 v18, s24, v125
	v_add_u32_e32 v2, s23, v108
	v_or_b32_e32 v19, 16, v18
	s_waitcnt lgkmcnt(0)
	v_ashrrev_i32_e32 v3, 31, v2
	v_max_i32_e32 v19, 3, v19
	v_lshl_add_u64 v[4:5], v[2:3], 1, s[10:11]
	v_add_u32_e32 v19, -3, v19
	v_lshlrev_b64 v[2:3], 2, v[2:3]
	v_max_i32_e32 v6, 3, v18
	v_mad_u64_u32 v[22:23], s[6:7], v19, s48, v[4:5]
	v_lshl_add_u64 v[58:59], s[4:5], 0, v[2:3]
	v_lshl_add_u64 v[62:63], s[8:9], 0, v[2:3]
	v_add_u32_e32 v2, 17, v18
	v_add_u32_e32 v19, 18, v18
	v_add_u32_e32 v6, -3, v6
	v_max_i32_e32 v8, 2, v18
	v_max_i32_e32 v14, 1, v18
	v_max_i32_e32 v2, 3, v2
	v_max_i32_e32 v19, 3, v19
	v_mad_u64_u32 v[6:7], s[6:7], v6, s48, v[4:5]
	v_add_u32_e32 v8, -2, v8
	v_add_u32_e32 v14, -1, v14
	v_max_i32_e32 v16, 0, v18
	v_add_u32_e32 v2, -3, v2
	v_add_u32_e32 v19, -3, v19
	global_load_dwordx4 v[10:13], v[6:7], off
	v_mad_u64_u32 v[8:9], s[6:7], v8, s48, v[4:5]
	v_mad_u64_u32 v[14:15], s[6:7], v14, s48, v[4:5]
	v_mad_u64_u32 v[16:17], s[6:7], v16, s48, v[4:5]
	v_mad_u64_u32 v[2:3], s[6:7], v2, s48, v[4:5]
	v_mad_u64_u32 v[24:25], s[6:7], v19, s48, v[4:5]
	v_add_u32_e32 v18, 19, v18
	s_movk_i32 s1, 0x2000
	global_load_dwordx4 v[86:89], v[8:9], off
	v_max_i32_e32 v18, 3, v18
	v_add_co_u32_e32 v26, vcc, s1, v58
	s_mov_b64 s[6:7], 0x1000
	global_load_dwordx4 v[90:93], v[14:15], off
	global_load_dwordx4 v[98:101], v[58:59], off offset:16
	global_load_dwordx4 v[102:105], v[58:59], off
	global_load_dwordx4 v[116:119], v[62:63], off offset:16
	global_load_dwordx4 v[120:123], v[62:63], off
	v_add_u32_e32 v20, -3, v18
	v_addc_co_u32_e32 v27, vcc, 0, v59, vcc
	v_lshl_add_u64 v[18:19], v[58:59], 0, s[6:7]
	global_load_dwordx4 v[126:129], v[26:27], off offset:-4096
	global_load_dwordx4 v[132:135], v[18:19], off offset:16
	global_load_dwordx4 v[136:139], v[26:27], off
	s_movk_i32 s1, 0x1000
	v_mad_u64_u32 v[4:5], s[6:7], v20, s48, v[4:5]
	v_add_co_u32_e32 v28, vcc, s1, v58
	s_mov_b64 s[6:7], 0x2000
	s_nop 0
	v_addc_co_u32_e32 v29, vcc, 0, v59, vcc
	s_movk_i32 s1, 0x3000
	v_lshl_add_u64 v[30:31], v[58:59], 0, s[6:7]
	s_mov_b64 s[6:7], 0x3000
	v_add_co_u32_e32 v60, vcc, s1, v58
	v_lshl_add_u64 v[32:33], v[58:59], 0, s[6:7]
	s_nop 0
	v_addc_co_u32_e32 v61, vcc, 0, v59, vcc
	global_load_dwordx4 v[18:21], v[60:61], off
	global_load_dwordx4 v[140:143], v[30:31], off offset:16
	global_load_dwordx4 v[82:85], v[32:33], off offset:16
	global_load_dwordx4 v[78:81], v[6:7], off offset:64
	global_load_dwordx4 v[74:77], v[8:9], off offset:64
	global_load_dwordx4 v[70:73], v[14:15], off offset:64
	global_load_dwordx4 v[144:147], v[16:17], off
	global_load_dwordx4 v[66:69], v[16:17], off offset:64
	global_load_dwordx4 v[148:151], v[22:23], off
	global_load_dwordx4 v[50:53], v[22:23], off offset:64
	global_load_dwordx4 v[152:155], v[2:3], off
	global_load_dwordx4 v[42:45], v[2:3], off offset:64
	global_load_dwordx4 v[156:159], v[24:25], off
	global_load_dwordx4 v[30:33], v[24:25], off offset:64
	global_load_dwordx4 v[160:163], v[4:5], off
	s_nop 0
	global_load_dwordx4 v[2:5], v[4:5], off offset:64
	s_nop 0
	global_load_dwordx4 v[46:49], v[58:59], off offset:144
	global_load_dwordx4 v[54:57], v[58:59], off offset:128
	s_mov_b64 s[6:7], 0x1080
	v_lshl_add_u64 v[6:7], v[58:59], 0, s[6:7]
	s_mov_b64 s[6:7], 0x2080
	v_lshl_add_u64 v[8:9], v[58:59], 0, s[6:7]
	s_mov_b64 s[6:7], 0x3080
	global_load_dwordx4 v[34:37], v[28:29], off offset:128
	global_load_dwordx4 v[22:25], v[26:27], off offset:128
	global_load_dwordx4 v[38:41], v[6:7], off offset:16
	s_nop 0
	global_load_dwordx4 v[26:29], v[8:9], off offset:16
	v_lshl_add_u64 v[6:7], v[58:59], 0, s[6:7]
	global_load_dwordx4 v[14:17], v[60:61], off offset:128
	s_nop 0
	global_load_dwordx4 v[6:9], v[6:7], off offset:16
	s_nop 0
	global_load_dwordx4 v[58:61], v[62:63], off offset:144
	s_nop 0
	global_load_dwordx4 v[62:65], v[62:63], off offset:128
	s_mov_b32 m0, 0x22000
	s_nop 0
	global_load_lds_dword v166, s[98:99]
	global_load_lds_dword v167, s[98:99] offset:2048
	s_and_b32 s22, s25, 31
	s_lshl_b32 s1, s22, 8
	s_add_i32 s1, s1, s26
	v_or_b32_e32 v97, s1, v125
	v_cmp_gt_u32_e32 vcc, 3, v97
	s_mov_b32 s1, 0x7fffffef
	s_lshl_b32 s0, s0, 13
	v_cndmask_b32_e64 v96, 1.0, 0, vcc
	v_cmp_gt_u32_e32 vcc, 2, v97
	v_readlane_b32 s7, v251, 18
	v_ashrrev_i32_e32 v109, 31, v108
	v_cndmask_b32_e64 v112, 1.0, 0, vcc
	v_cmp_eq_u32_e32 vcc, 0, v97
	v_lshlrev_b32_e32 v130, 7, v125
	v_or_b32_e32 v107, 32, v125
	s_waitcnt vmcnt(35)
	v_lshlrev_b32_e32 v94, 16, v10
	v_and_b32_e32 v95, 0xffff0000, v10
	v_lshlrev_b32_e32 v10, 16, v11
	v_and_b32_e32 v11, 0xffff0000, v11
	v_lshlrev_b32_e32 v110, 16, v12
	v_and_b32_e32 v111, 0xffff0000, v12
	v_lshlrev_b32_e32 v12, 16, v13
	v_and_b32_e32 v13, 0xffff0000, v13
	v_pk_mul_f32 v[94:95], v[96:97], v[94:95] op_sel_hi:[0,1]
	v_pk_mul_f32 v[10:11], v[96:97], v[10:11] op_sel_hi:[0,1]
	v_pk_mul_f32 v[110:111], v[96:97], v[110:111] op_sel_hi:[0,1]
	v_pk_mul_f32 v[12:13], v[96:97], v[12:13] op_sel_hi:[0,1]
	s_waitcnt vmcnt(34)
; __device__ __forceinline__ u32x4 pack8(f32x4 a, f32x4 b) { u32x4 w; w.x = cvtpk(a[0], a[1]); w.y = cvtpk(a[2], a[3]); w.z = cvtpk(b[0], b[1]); w.w = cvtpk(b[2], b[3]); return w; }
; __device__ __forceinline__ void unpack8(u32x4 w, f32x4& a, f32x4& b) { a = (f32x4){bf_lo(w.x), bf_hi(w.x), bf_lo(w.y), bf_hi(w.y)}; b = (f32x4){bf_lo(w.z), bf_hi(w.z), bf_lo(w.w), bf_hi(w.w)}; }
; template <bool FINAL, bool SMP>
; __device__ __forceinline__ void lru_unit(const Args& args, int l, int p, int h, LAS unsigned char* lds, int wave, int lane) {
;     ...
; #pragma unroll
;         for (int mt = 0; mt < 2; ++mt) {
;             f32x4 u0 = cbv[0][0], u1 = cbv[0][1];
; #pragma unroll
;             for (int k = 0; k < 4; ++k) {
;                 const int ts = t0 + 16 * mt + r16 + k - 3;
;                 f32x4 x0, x1; unpack8(xr[0][mt][k], x0, x1);
;                 if (!SMP) { const float keep = ts < 0 ? 0.f : 1.f; x0 = x0 * keep; x1 = x1 * keep; }
;                 u0 += cwv[0][k][0] * x0; u1 += cwv[0][k][1] * x1;
;             }
;             Af[mt][0] = __builtin_bit_cast(bf16x8, pack8(u0, u1));
;         }
	v_lshlrev_b32_e32 v114, 16, v86
	v_and_b32_e32 v115, 0xffff0000, v86
	v_lshlrev_b32_e32 v86, 16, v87
	v_and_b32_e32 v87, 0xffff0000, v87
	v_lshlrev_b32_e32 v164, 16, v88
	v_and_b32_e32 v165, 0xffff0000, v88
	v_lshlrev_b32_e32 v88, 16, v89
	v_and_b32_e32 v89, 0xffff0000, v89
	s_waitcnt vmcnt(29)
	v_pk_fma_f32 v[10:11], v[104:105], v[10:11], v[122:123]
	v_pk_fma_f32 v[94:95], v[102:103], v[94:95], v[120:121]
	v_pk_fma_f32 v[12:13], v[12:13], v[100:101], v[118:119]
	v_pk_fma_f32 v[110:111], v[110:111], v[98:99], v[116:117]
	v_pk_mul_f32 v[114:115], v[112:113], v[114:115] op_sel_hi:[0,1]
	v_pk_mul_f32 v[86:87], v[112:113], v[86:87] op_sel_hi:[0,1]
	v_pk_mul_f32 v[164:165], v[112:113], v[164:165] op_sel_hi:[0,1]
	v_pk_mul_f32 v[88:89], v[112:113], v[88:89] op_sel_hi:[0,1]
	s_waitcnt vmcnt(28)
	v_pk_fma_f32 v[10:11], v[86:87], v[128:129], v[10:11]
	v_pk_fma_f32 v[86:87], v[114:115], v[126:127], v[94:95]
	s_waitcnt vmcnt(27)
	v_pk_fma_f32 v[12:13], v[88:89], v[134:135], v[12:13]
	v_pk_fma_f32 v[88:89], v[164:165], v[132:133], v[110:111]
	v_lshlrev_b32_e32 v94, 16, v90
	v_and_b32_e32 v95, 0xffff0000, v90
	v_lshlrev_b32_e32 v90, 16, v91
	v_and_b32_e32 v91, 0xffff0000, v91
	v_lshlrev_b32_e32 v110, 16, v92
	v_and_b32_e32 v111, 0xffff0000, v92
	v_lshlrev_b32_e32 v92, 16, v93
	v_and_b32_e32 v93, 0xffff0000, v93
	v_cndmask_b32_e64 v114, 1.0, 0, vcc
	v_pk_mul_f32 v[90:91], v[114:115], v[90:91] op_sel_hi:[0,1]
	v_pk_mul_f32 v[94:95], v[114:115], v[94:95] op_sel_hi:[0,1]
	v_pk_mul_f32 v[110:111], v[114:115], v[110:111] op_sel_hi:[0,1]
	v_pk_mul_f32 v[92:93], v[114:115], v[92:93] op_sel_hi:[0,1]
	s_waitcnt vmcnt(26)
	v_pk_fma_f32 v[86:87], v[94:95], v[136:137], v[86:87]
	v_pk_fma_f32 v[10:11], v[90:91], v[138:139], v[10:11]
	s_waitcnt vmcnt(24)
	v_pk_fma_f32 v[12:13], v[92:93], v[142:143], v[12:13]
	v_pk_fma_f32 v[88:89], v[110:111], v[140:141], v[88:89]
	s_waitcnt vmcnt(19)
	v_lshlrev_b32_e32 v90, 16, v144
	v_and_b32_e32 v91, 0xffff0000, v144
	v_lshlrev_b32_e32 v92, 16, v145
	v_and_b32_e32 v93, 0xffff0000, v145
	v_lshlrev_b32_e32 v94, 16, v146
	v_and_b32_e32 v95, 0xffff0000, v146
	v_lshlrev_b32_e32 v110, 16, v147
	v_and_b32_e32 v111, 0xffff0000, v147
	v_pk_fma_f32 v[92:93], v[20:21], v[92:93], v[10:11]
	v_pk_fma_f32 v[10:11], v[18:19], v[90:91], v[86:87]
	v_pk_fma_f32 v[86:87], v[84:85], v[110:111], v[12:13]
	v_pk_fma_f32 v[12:13], v[82:83], v[94:95], v[88:89]
	v_cvt_pk_bf16_f32 v10, v10, v11
	v_cvt_pk_bf16_f32 v11, v92, v93
	v_cvt_pk_bf16_f32 v12, v12, v13
	v_cvt_pk_bf16_f32 v13, v86, v87
	s_waitcnt vmcnt(17)
	v_lshlrev_b32_e32 v86, 16, v148
	v_and_b32_e32 v87, 0xffff0000, v148
	v_lshlrev_b32_e32 v90, 16, v150
	v_and_b32_e32 v91, 0xffff0000, v150
	v_lshlrev_b32_e32 v92, 16, v151
	v_and_b32_e32 v93, 0xffff0000, v151
	v_cmp_eq_u32_e32 vcc, s1, v97
	v_lshlrev_b32_e32 v88, 16, v149
	v_and_b32_e32 v89, 0xffff0000, v149
	v_pk_fma_f32 v[86:87], v[102:103], v[86:87], v[120:121]
	v_pk_fma_f32 v[92:93], v[100:101], v[92:93], v[118:119]
	v_pk_fma_f32 v[90:91], v[98:99], v[90:91], v[116:117]
	s_waitcnt vmcnt(15)
	v_lshlrev_b32_e32 v94, 16, v152
	v_and_b32_e32 v95, 0xffff0000, v152
	v_lshlrev_b32_e32 v98, 16, v153
	v_and_b32_e32 v99, 0xffff0000, v153
	v_lshlrev_b32_e32 v100, 16, v154
	v_and_b32_e32 v101, 0xffff0000, v154
	v_lshlrev_b32_e32 v102, 16, v155
	v_and_b32_e32 v103, 0xffff0000, v155
	v_cndmask_b32_e64 v116, 1.0, 0, vcc
	s_mov_b32 s1, 0x7fffffed
	v_pk_fma_f32 v[88:89], v[104:105], v[88:89], v[122:123]
	v_pk_mul_f32 v[94:95], v[116:117], v[94:95] op_sel_hi:[0,1]
	v_pk_mul_f32 v[98:99], v[116:117], v[98:99] op_sel_hi:[0,1]
	v_pk_mul_f32 v[100:101], v[116:117], v[100:101] op_sel_hi:[0,1]
	v_pk_mul_f32 v[102:103], v[116:117], v[102:103] op_sel_hi:[0,1]
	v_cmp_lt_u32_e32 vcc, s1, v97
	s_mov_b32 s1, 0x7fffffec
	v_pk_fma_f32 v[88:89], v[128:129], v[98:99], v[88:89]
	v_pk_fma_f32 v[86:87], v[126:127], v[94:95], v[86:87]
	v_pk_fma_f32 v[92:93], v[134:135], v[102:103], v[92:93]
	v_pk_fma_f32 v[90:91], v[132:133], v[100:101], v[90:91]
	s_waitcnt vmcnt(13)
	v_lshlrev_b32_e32 v94, 16, v156
	v_and_b32_e32 v95, 0xffff0000, v156
	v_lshlrev_b32_e32 v98, 16, v157
	v_and_b32_e32 v99, 0xffff0000, v157
	v_lshlrev_b32_e32 v100, 16, v158
	v_and_b32_e32 v101, 0xffff0000, v158
	v_lshlrev_b32_e32 v102, 16, v159
	v_and_b32_e32 v103, 0xffff0000, v159
	v_cndmask_b32_e64 v118, 1.0, 0, vcc
	v_cmp_lt_u32_e32 vcc, s1, v97
	s_lshl_b32 s1, s42, 1
	v_pk_mul_f32 v[98:99], v[118:119], v[98:99] op_sel_hi:[0,1]
	v_pk_mul_f32 v[94:95], v[118:119], v[94:95] op_sel_hi:[0,1]
	v_pk_mul_f32 v[100:101], v[118:119], v[100:101] op_sel_hi:[0,1]
	v_pk_mul_f32 v[102:103], v[118:119], v[102:103] op_sel_hi:[0,1]
	s_or_b32 s6, s0, s1
	v_readlane_b32 s0, v251, 16
	v_pk_fma_f32 v[86:87], v[136:137], v[94:95], v[86:87]
	v_pk_fma_f32 v[88:89], v[138:139], v[98:99], v[88:89]
	v_pk_fma_f32 v[92:93], v[142:143], v[102:103], v[92:93]
	v_pk_fma_f32 v[90:91], v[140:141], v[100:101], v[90:91]
	s_waitcnt vmcnt(11)
; __device__ __forceinline__ u32x4 pack8(f32x4 a, f32x4 b) { u32x4 w; w.x = cvtpk(a[0], a[1]); w.y = cvtpk(a[2], a[3]); w.z = cvtpk(b[0], b[1]); w.w = cvtpk(b[2], b[3]); return w; }
; __device__ __forceinline__ void unpack8(u32x4 w, f32x4& a, f32x4& b) { a = (f32x4){bf_lo(w.x), bf_hi(w.x), bf_lo(w.y), bf_hi(w.y)}; b = (f32x4){bf_lo(w.z), bf_hi(w.z), bf_lo(w.w), bf_hi(w.w)}; }
; template <bool FINAL, bool SMP>
; __device__ __forceinline__ void lru_unit(const Args& args, int l, int p, int h, LAS unsigned char* lds, int wave, int lane) {
;     ...
;         }
;     asm volatile("" ::: "memory");
;     bf16x8 fa[4][2], fi[4][2];
;     float bav[4], biv[4], lamv[4];
;     {
;         const bf16_t* WAT = (const bf16_t*)(ws + WS_WAT) + ((size_t)(l * LHEADS + h) * 64) * 64;
;         const bf16_t* WIT = (const bf16_t*)(ws + WS_WIT) + ((size_t)(l * LHEADS + h) * 64) * 64;
;         const float* ba = args.in[I_LBA] + (size_t)l * LW; const float* bi = args.in[I_LBI] + (size_t)l * LW; const float* c8t = (const float*)(ws + WS_PA) + (size_t)l * LW;
; #pragma unroll
;         for (int nt = 0; nt < 4; ++nt) {
; #pragma unroll
;             for (int ks = 0; ks < 2; ++ks) { const int n = 16 * nt + r16, k0 = 32 * ks + 8 * g; fa[nt][ks] = *(const bf16x8*)(WAT + n * 64 + k0); fi[nt][ks] = *(const bf16x8*)(WIT + n * 64 + k0); }
;             const int ch = h * 64 + 16 * nt + r16; bav[nt] = ba[ch]; biv[nt] = bi[ch]; lamv[nt] = c8t[ch];
;         }
;     }
;     asm volatile("" ::: "memory");
; #pragma unroll
;         for (int mt = 0; mt < 2; ++mt) {
;             f32x4 u0 = cbv[1][0], u1 = cbv[1][1];
; #pragma unroll
;             for (int k = 0; k < 4; ++k) {
;                 const int ts = t0 + 16 * mt + r16 + k - 3;
;                 f32x4 x0, x1; unpack8(xr[1][mt][k], x0, x1);
;                 if (!SMP) { const float keep = ts < 0 ? 0.f : 1.f; x0 = x0 * keep; x1 = x1 * keep; }
;                 u0 += cwv[1][k][0] * x0; u1 += cwv[1][k][1] * x1;
;             }
;             Af[mt][1] = __builtin_bit_cast(bf16x8, pack8(u0, u1));
;         }
	v_lshlrev_b32_e32 v98, 16, v160
	v_and_b32_e32 v99, 0xffff0000, v160
	v_lshlrev_b32_e32 v100, 16, v161
	v_and_b32_e32 v101, 0xffff0000, v161
	v_lshlrev_b32_e32 v102, 16, v162
	v_and_b32_e32 v103, 0xffff0000, v162
	v_cndmask_b32_e64 v94, 1.0, 0, vcc
	s_add_u32 s0, s0, s6
	v_readlane_b32 s1, v251, 17
	v_lshlrev_b32_e32 v104, 16, v163
	v_and_b32_e32 v105, 0xffff0000, v163
	v_pk_mul_f32 v[98:99], v[94:95], v[98:99] op_sel_hi:[0,1]
	v_pk_mul_f32 v[100:101], v[94:95], v[100:101] op_sel_hi:[0,1]
	v_pk_mul_f32 v[102:103], v[94:95], v[102:103] op_sel_hi:[0,1]
	s_addc_u32 s1, s1, 0
	v_pk_mul_f32 v[104:105], v[94:95], v[104:105] op_sel_hi:[0,1]
	v_pk_fma_f32 v[20:21], v[20:21], v[100:101], v[88:89]
	v_pk_fma_f32 v[18:19], v[18:19], v[98:99], v[86:87]
	v_pk_fma_f32 v[82:83], v[82:83], v[102:103], v[90:91]
	s_add_u32 s6, s7, s6
	v_readlane_b32 s7, v251, 19
	v_pk_fma_f32 v[84:85], v[84:85], v[104:105], v[92:93]
	v_cvt_pk_bf16_f32 v18, v18, v19
	v_cvt_pk_bf16_f32 v19, v20, v21
	v_cvt_pk_bf16_f32 v20, v82, v83
	s_addc_u32 s7, s7, 0
	v_lshl_add_u64 v[82:83], s[0:1], 0, v[130:131]
	v_lshlrev_b64 v[110:111], 1, v[108:109]
	v_cvt_pk_bf16_f32 v21, v84, v85
	v_lshl_add_u64 v[84:85], s[6:7], 0, v[130:131]
	v_lshl_add_u64 v[122:123], v[82:83], 0, v[110:111]
	v_lshl_add_u64 v[120:121], v[84:85], 0, v[110:111]
	global_load_dwordx4 v[82:85], v[122:123], off
	global_load_dwordx4 v[98:101], v[122:123], off offset:64
	global_load_dwordx4 v[86:89], v[120:121], off
	global_load_dwordx4 v[102:105], v[120:121], off offset:64
	global_load_dwordx4 v[90:93], v[122:123], off offset:2048
	v_lshlrev_b32_e32 v126, 16, v78
	v_and_b32_e32 v127, 0xffff0000, v78
	v_lshlrev_b32_e32 v128, 16, v80
	v_and_b32_e32 v129, 0xffff0000, v80
	v_lshlrev_b32_e32 v78, 16, v79
	v_and_b32_e32 v79, 0xffff0000, v79
	v_lshlrev_b32_e32 v80, 16, v81
	v_and_b32_e32 v81, 0xffff0000, v81
	v_pk_mul_f32 v[126:127], v[96:97], v[126:127] op_sel_hi:[0,1]
	v_pk_mul_f32 v[128:129], v[96:97], v[128:129] op_sel_hi:[0,1]
	v_pk_mul_f32 v[78:79], v[96:97], v[78:79] op_sel_hi:[0,1]
	v_pk_mul_f32 v[80:81], v[96:97], v[80:81] op_sel_hi:[0,1]
	s_waitcnt vmcnt(5)
	v_pk_fma_f32 v[96:97], v[54:55], v[126:127], v[62:63]
	v_pk_fma_f32 v[126:127], v[128:129], v[46:47], v[58:59]
	v_lshlrev_b32_e32 v128, 16, v74
	v_and_b32_e32 v129, 0xffff0000, v74
	v_lshlrev_b32_e32 v74, 16, v75
	v_and_b32_e32 v75, 0xffff0000, v75
	v_pk_fma_f32 v[78:79], v[56:57], v[78:79], v[64:65]
	v_lshlrev_b32_e32 v132, 16, v76
	v_and_b32_e32 v133, 0xffff0000, v76
	v_lshlrev_b32_e32 v76, 16, v77
	v_and_b32_e32 v77, 0xffff0000, v77
	v_pk_mul_f32 v[128:129], v[112:113], v[128:129] op_sel_hi:[0,1]
	v_pk_mul_f32 v[74:75], v[112:113], v[74:75] op_sel_hi:[0,1]
	v_pk_fma_f32 v[80:81], v[80:81], v[48:49], v[60:61]
	v_pk_mul_f32 v[132:133], v[112:113], v[132:133] op_sel_hi:[0,1]
	v_pk_mul_f32 v[76:77], v[112:113], v[76:77] op_sel_hi:[0,1]
	v_pk_fma_f32 v[74:75], v[74:75], v[36:37], v[78:79]
	v_pk_fma_f32 v[78:79], v[128:129], v[34:35], v[96:97]
	v_lshlrev_b32_e32 v96, 16, v70
	v_and_b32_e32 v97, 0xffff0000, v70
	v_lshlrev_b32_e32 v70, 16, v71
	v_and_b32_e32 v71, 0xffff0000, v71
	v_lshlrev_b32_e32 v112, 16, v72
	v_and_b32_e32 v113, 0xffff0000, v72
	v_lshlrev_b32_e32 v72, 16, v73
	v_and_b32_e32 v73, 0xffff0000, v73
	v_pk_fma_f32 v[76:77], v[76:77], v[40:41], v[80:81]
	v_pk_fma_f32 v[80:81], v[132:133], v[38:39], v[126:127]
	v_pk_mul_f32 v[70:71], v[114:115], v[70:71] op_sel_hi:[0,1]
	v_pk_mul_f32 v[112:113], v[114:115], v[112:113] op_sel_hi:[0,1]
	v_pk_mul_f32 v[72:73], v[114:115], v[72:73] op_sel_hi:[0,1]
	v_pk_mul_f32 v[96:97], v[114:115], v[96:97] op_sel_hi:[0,1]
	v_pk_fma_f32 v[70:71], v[70:71], v[24:25], v[74:75]
	v_pk_fma_f32 v[72:73], v[72:73], v[28:29], v[76:77]
	v_pk_fma_f32 v[74:75], v[112:113], v[26:27], v[80:81]
	v_lshlrev_b32_e32 v76, 16, v66
	v_and_b32_e32 v77, 0xffff0000, v66
	v_lshlrev_b32_e32 v66, 16, v67
	v_and_b32_e32 v67, 0xffff0000, v67
	v_lshlrev_b32_e32 v80, 16, v68
	v_and_b32_e32 v81, 0xffff0000, v68
	v_lshlrev_b32_e32 v68, 16, v69
	v_and_b32_e32 v69, 0xffff0000, v69
	v_pk_fma_f32 v[78:79], v[96:97], v[22:23], v[78:79]
	v_pk_fma_f32 v[66:67], v[16:17], v[66:67], v[70:71]
	v_pk_fma_f32 v[68:69], v[8:9], v[68:69], v[72:73]
	v_pk_fma_f32 v[70:71], v[14:15], v[76:77], v[78:79]
	v_pk_fma_f32 v[72:73], v[6:7], v[80:81], v[74:75]
	v_cvt_pk_bf16_f32 v75, v66, v67
	v_cvt_pk_bf16_f32 v77, v68, v69
	v_lshlrev_b32_e32 v66, 16, v50
	v_and_b32_e32 v67, 0xffff0000, v50
	v_lshlrev_b32_e32 v50, 16, v51
	v_and_b32_e32 v51, 0xffff0000, v51
	v_lshlrev_b32_e32 v68, 16, v52
	v_and_b32_e32 v69, 0xffff0000, v52
	v_lshlrev_b32_e32 v52, 16, v53
	v_and_b32_e32 v53, 0xffff0000, v53
	v_pk_fma_f32 v[50:51], v[56:57], v[50:51], v[64:65]
	v_pk_fma_f32 v[48:49], v[48:49], v[52:53], v[60:61]
	v_lshlrev_b32_e32 v52, 16, v42
	v_and_b32_e32 v53, 0xffff0000, v42
	v_lshlrev_b32_e32 v42, 16, v43
	v_and_b32_e32 v43, 0xffff0000, v43
	v_lshlrev_b32_e32 v56, 16, v44
	v_and_b32_e32 v57, 0xffff0000, v44
	v_lshlrev_b32_e32 v44, 16, v45
	v_and_b32_e32 v45, 0xffff0000, v45
	v_pk_mul_f32 v[42:43], v[116:117], v[42:43] op_sel_hi:[0,1]
	v_pk_mul_f32 v[44:45], v[116:117], v[44:45] op_sel_hi:[0,1]
	v_pk_fma_f32 v[54:55], v[54:55], v[66:67], v[62:63]
	v_pk_mul_f32 v[52:53], v[116:117], v[52:53] op_sel_hi:[0,1]
	v_pk_fma_f32 v[36:37], v[36:37], v[42:43], v[50:51]
	v_pk_fma_f32 v[40:41], v[40:41], v[44:45], v[48:49]
	v_lshlrev_b32_e32 v42, 16, v30
	v_and_b32_e32 v43, 0xffff0000, v30
	v_lshlrev_b32_e32 v30, 16, v31
	v_and_b32_e32 v31, 0xffff0000, v31
	v_lshlrev_b32_e32 v44, 16, v32
	v_and_b32_e32 v45, 0xffff0000, v32
	v_lshlrev_b32_e32 v32, 16, v33
	v_and_b32_e32 v33, 0xffff0000, v33
; __device__ __forceinline__ u32x4 pack8(f32x4 a, f32x4 b) { u32x4 w; w.x = cvtpk(a[0], a[1]); w.y = cvtpk(a[2], a[3]); w.z = cvtpk(b[0], b[1]); w.w = cvtpk(b[2], b[3]); return w; }
; template <bool FINAL, bool SMP>
; __device__ __forceinline__ void lru_unit(const Args& args, int l, int p, int h, LAS unsigned char* lds, int wave, int lane) {
;     ...
; #pragma unroll
;         for (int nt = 0; nt < 4; ++nt) {
; #pragma unroll
;             for (int ks = 0; ks < 2; ++ks) { const int n = 16 * nt + r16, k0 = 32 * ks + 8 * g; fa[nt][ks] = *(const bf16x8*)(WAT + n * 64 + k0); fi[nt][ks] = *(const bf16x8*)(WIT + n * 64 + k0); }
;             const int ch = h * 64 + 16 * nt + r16; bav[nt] = ba[ch]; biv[nt] = bi[ch]; lamv[nt] = c8t[ch];
;         }
;     }
;     asm volatile("" ::: "memory");
; #pragma unroll
;         for (int mt = 0; mt < 2; ++mt) {
;             f32x4 u0 = cbv[1][0], u1 = cbv[1][1];
; #pragma unroll
;             for (int k = 0; k < 4; ++k) {
;                 const int ts = t0 + 16 * mt + r16 + k - 3;
;                 f32x4 x0, x1; unpack8(xr[1][mt][k], x0, x1);
;                 if (!SMP) { const float keep = ts < 0 ? 0.f : 1.f; x0 = x0 * keep; x1 = x1 * keep; }
;                 u0 += cwv[1][k][0] * x0; u1 += cwv[1][k][1] * x1;
;             }
;             Af[mt][1] = __builtin_bit_cast(bf16x8, pack8(u0, u1));
;         }
;     f32x4 Da[2][4], Di[2][4], Du[2][4];
; #pragma unroll
;     for (int nt = 0; nt < 4; ++nt) {
; #pragma unroll
;         for (int mt = 0; mt < 2; ++mt) { Da[mt][nt] = (f32x4){0.f, 0.f, 0.f, 0.f}; Di[mt][nt] = Da[mt][nt]; Du[mt][nt] = Da[mt][nt]; }
; #pragma unroll
;         for (int ks = 0; ks < 2; ++ks) {
;             const int n = 16 * nt + r16, k0 = 32 * ks + 8 * g;
;             bf16x8 id;
; #pragma unroll
;             for (int j = 0; j < 8; ++j) id[j] = (k0 + j == n) ? (short)0x3F80 : (short)0;
; #pragma unroll
;             for (int mt = 0; mt < 2; ++mt) {
;                 Da[mt][nt] = __builtin_amdgcn_mfma_f32_16x16x32_bf16(Af[mt][ks], fa[nt][ks], Da[mt][nt], 0, 0, 0);
;                 Di[mt][nt] = __builtin_amdgcn_mfma_f32_16x16x32_bf16(Af[mt][ks], fi[nt][ks], Di[mt][nt], 0, 0, 0);
;                 Du[mt][nt] = __builtin_amdgcn_mfma_f32_16x16x32_bf16(Af[mt][ks], id, Du[mt][nt], 0, 0, 0);
;             }
;         }
;     }
	v_pk_fma_f32 v[46:47], v[46:47], v[68:69], v[58:59]
	v_pk_mul_f32 v[56:57], v[116:117], v[56:57] op_sel_hi:[0,1]
	v_pk_fma_f32 v[34:35], v[34:35], v[52:53], v[54:55]
	v_pk_mul_f32 v[30:31], v[118:119], v[30:31] op_sel_hi:[0,1]
	v_pk_mul_f32 v[42:43], v[118:119], v[42:43] op_sel_hi:[0,1]
	v_pk_mul_f32 v[32:33], v[118:119], v[32:33] op_sel_hi:[0,1]
	v_pk_fma_f32 v[38:39], v[38:39], v[56:57], v[46:47]
	v_pk_mul_f32 v[44:45], v[118:119], v[44:45] op_sel_hi:[0,1]
	v_pk_fma_f32 v[34:35], v[22:23], v[42:43], v[34:35]
	v_pk_fma_f32 v[30:31], v[24:25], v[30:31], v[36:37]
	v_pk_fma_f32 v[36:37], v[28:29], v[32:33], v[40:41]
	v_lshlrev_b32_e32 v40, 16, v4
	v_and_b32_e32 v41, 0xffff0000, v4
	v_lshlrev_b32_e32 v42, 16, v5
	v_and_b32_e32 v43, 0xffff0000, v5
	v_pk_fma_f32 v[38:39], v[26:27], v[44:45], v[38:39]
	v_pk_mul_f32 v[40:41], v[94:95], v[40:41] op_sel_hi:[0,1]
	v_pk_mul_f32 v[42:43], v[94:95], v[42:43] op_sel_hi:[0,1]
	v_pk_fma_f32 v[8:9], v[8:9], v[42:43], v[36:37]
	v_pk_fma_f32 v[6:7], v[6:7], v[40:41], v[38:39]
	v_cvt_pk_bf16_f32 v97, v8, v9
	v_cvt_pk_bf16_f32 v96, v6, v7
	global_load_dwordx4 v[6:9], v[122:123], off offset:2112
	v_lshlrev_b32_e32 v32, 16, v2
	v_and_b32_e32 v33, 0xffff0000, v2
	v_lshlrev_b32_e32 v2, 16, v3
	v_and_b32_e32 v3, 0xffff0000, v3
	v_pk_mul_f32 v[44:45], v[94:95], v[32:33] op_sel_hi:[0,1]
	v_pk_mul_f32 v[32:33], v[94:95], v[2:3] op_sel_hi:[0,1]
	v_pk_fma_f32 v[16:17], v[16:17], v[32:33], v[30:31]
	v_pk_fma_f32 v[14:15], v[14:15], v[44:45], v[34:35]
	v_cvt_pk_bf16_f32 v95, v16, v17
	v_cvt_pk_bf16_f32 v94, v14, v15
	s_waitcnt vmcnt(5)
	v_mfma_f32_16x16x32_bf16 v[2:5], v[18:21], v[82:85], 0
	v_cvt_pk_bf16_f32 v74, v70, v71
	v_cvt_pk_bf16_f32 v76, v72, v73
	v_or_b32_e32 v38, 0x1000, v130
	s_waitcnt vmcnt(3)
	v_mfma_f32_16x16x32_bf16 v[30:33], v[18:21], v[86:89], 0
	v_mov_b32_e32 v39, v131
	v_or_b32_e32 v130, 0x1800, v130
	v_cmp_eq_u32_e32 vcc, v108, v125
	v_mfma_f32_16x16x32_bf16 v[22:25], v[10:13], v[82:85], 0
	v_or_b32_e32 v118, 4, v108
	v_or_b32_e32 v119, 3, v108
	v_or_b32_e32 v126, 6, v108
	v_mfma_f32_16x16x32_bf16 v[70:73], v[94:97], v[98:101], v[2:5]
	v_or_b32_e32 v127, 5, v108
	v_add_u32_e32 v155, 35, v108
	v_add_u32_e32 v156, 36, v108
	global_load_dwordx4 v[2:5], v[120:121], off offset:2048
	s_waitcnt vmcnt(3)
	v_mfma_f32_16x16x32_bf16 v[66:69], v[94:97], v[102:105], v[30:33]
	v_add_u32_e32 v159, 37, v108
	s_nop 1
	v_lshl_add_u64 v[30:31], s[0:1], 0, v[38:39]
	v_lshl_add_u64 v[38:39], s[6:7], 0, v[38:39]
	v_lshl_add_u64 v[42:43], v[30:31], 0, v[110:111]
	v_lshl_add_u64 v[44:45], v[38:39], 0, v[110:111]
	v_mfma_f32_16x16x32_bf16 v[26:29], v[10:13], v[86:89], 0
	global_load_dwordx4 v[34:37], v[42:43], off
	global_load_dwordx4 v[50:53], v[42:43], off offset:64
	global_load_dwordx4 v[38:41], v[44:45], off
	global_load_dwordx4 v[62:65], v[44:45], off offset:64
	v_mfma_f32_16x16x32_bf16 v[86:89], v[74:77], v[98:101], v[22:25]
	s_nop 2
	global_load_dwordx4 v[22:25], v[120:121], off offset:2112
	s_waitcnt vmcnt(7)
	v_mfma_f32_16x16x32_bf16 v[14:17], v[10:13], v[90:93], 0
	v_mfma_f32_16x16x32_bf16 v[30:33], v[18:21], v[90:93], 0
	s_waitcnt vmcnt(6)
	v_mfma_f32_16x16x32_bf16 v[58:61], v[74:77], v[6:9], v[14:17]
	s_nop 4
	v_lshl_add_u64 v[14:15], s[6:7], 0, v[130:131]
	v_lshl_add_u64 v[14:15], v[14:15], 0, v[110:111]
	v_mfma_f32_16x16x32_bf16 v[46:49], v[94:97], v[6:9], v[30:33]
	v_or_b32_e32 v6, s23, v125
	v_lshlrev_b32_e32 v122, 2, v6
	v_lshl_add_u64 v[6:7], s[0:1], 0, v[130:131]
	v_lshl_add_u64 v[16:17], v[6:7], 0, v[110:111]
	global_load_dword v113, v122, s[16:17]
	global_load_dword v112, v122, s[36:37]
	global_load_dword v123, v122, s[62:63]
	global_load_dwordx4 v[30:33], v[16:17], off
	global_load_dwordx4 v[98:101], v[16:17], off offset:64
	global_load_dwordx4 v[78:81], v[14:15], off
	s_nop 0
	global_load_dwordx4 v[14:17], v[14:15], off offset:64
	v_mfma_f32_16x16x32_bf16 v[82:85], v[74:77], v[102:105], v[26:29]
	v_or_b32_e32 v104, 7, v108
	v_cndmask_b32_e32 v103, 0, v205, vcc
	v_cmp_eq_u32_e32 vcc, v104, v125
	s_waitcnt vmcnt(12)
	v_mfma_f32_16x16x32_bf16 v[26:29], v[10:13], v[2:5], 0
	v_or_b32_e32 v105, 16, v125
	v_cndmask_b32_e32 v90, 0, v205, vcc
	v_cmp_eq_u32_e32 vcc, v108, v105
	v_mfma_f32_16x16x32_bf16 v[2:5], v[18:21], v[2:5], 0
	v_or_b32_e32 v110, 48, v125
	v_cndmask_b32_e32 v91, 0, v205, vcc
	v_cmp_eq_u32_e32 vcc, v104, v105
	s_waitcnt vmcnt(7)
	v_mfma_f32_16x16x32_bf16 v[42:45], v[94:97], v[22:25], v[2:5]
	v_cndmask_b32_e32 v92, 0, v205, vcc
	v_cmp_eq_u32_e32 vcc, v108, v107
	v_add_u32_e32 v102, 32, v108
	v_mfma_f32_16x16x32_bf16 v[2:5], v[10:13], v[34:37], 0
	v_cndmask_b32_e32 v109, 0, v205, vcc
	v_cmp_eq_u32_e32 vcc, v104, v107
	s_waitcnt vmcnt(6)
	v_add_f32_e32 v70, v113, v70
	v_mfma_f32_16x16x32_bf16 v[6:9], v[10:13], v[38:41], 0
	v_cndmask_b32_e32 v93, 0, v205, vcc
	v_cmp_eq_u32_e32 vcc, v108, v110
	s_waitcnt vmcnt(5)
	v_add_f32_e32 v83, v112, v83
	v_mfma_f32_16x16x32_bf16 v[34:37], v[18:21], v[34:37], 0
	v_cndmask_b32_e32 v111, 0, v205, vcc
	v_mul_f32_e32 v83, 0xbfb8aa3b, v83
	v_exp_f32_e32 v83, v83
	v_mfma_f32_16x16x32_bf16 v[54:57], v[74:77], v[22:25], v[26:29]
	v_add_f32_e32 v84, v112, v84
	v_mul_f32_e32 v84, 0xbfb8aa3b, v84
	v_exp_f32_e32 v84, v84
	v_mfma_f32_16x16x32_bf16 v[22:25], v[74:77], v[62:65], v[6:9]
	v_add_f32_e32 v85, v112, v85
	v_mul_f32_e32 v85, 0xbfb8aa3b, v85
	v_exp_f32_e32 v85, v85
	v_mfma_f32_16x16x32_bf16 v[6:9], v[94:97], v[50:53], v[34:37]
	v_mul_f32_e32 v70, 0xbfb8aa3b, v70
	v_exp_f32_e32 v70, v70
	v_add_f32_e32 v66, v112, v66
	v_or_b32_e32 v35, 2, v108
	v_or_b32_e32 v36, 1, v108
	v_cmp_eq_u32_e32 vcc, v35, v125
	v_mfma_f32_16x16x32_bf16 v[26:29], v[74:77], v[50:53], v[2:5]
	v_add_f32_e32 v70, 1.0, v70
	v_cndmask_b32_e32 v37, 0, v205, vcc
	v_cmp_eq_u32_e32 vcc, v36, v125
	v_mfma_f32_16x16x32_bf16 v[38:41], v[18:21], v[38:41], 0
	v_rcp_f32_e32 v70, v70
	v_cndmask_b32_e32 v34, 0, v205, vcc
	v_cmp_eq_u32_e32 vcc, v36, v105
	v_mfma_f32_16x16x32_bf16 v[2:5], v[94:97], v[62:65], v[38:41]
	v_perm_b32 v34, v34, v103, s50
	v_cndmask_b32_e32 v50, 0, v205, vcc
	v_cmp_eq_u32_e32 vcc, v35, v105
	v_perm_b32 v50, v50, v91, s50
	s_waitcnt vmcnt(1)
; template <bool FINAL, bool SMP>
; __device__ __forceinline__ void lru_unit(const Args& args, int l, int p, int h, LAS unsigned char* lds, int wave, int lane) {
;     ...
;     f32x4 Da[2][4], Di[2][4], Du[2][4];
; #pragma unroll
;     for (int nt = 0; nt < 4; ++nt) {
; #pragma unroll
;         for (int mt = 0; mt < 2; ++mt) { Da[mt][nt] = (f32x4){0.f, 0.f, 0.f, 0.f}; Di[mt][nt] = Da[mt][nt]; Du[mt][nt] = Da[mt][nt]; }
; #pragma unroll
;         for (int ks = 0; ks < 2; ++ks) {
;             const int n = 16 * nt + r16, k0 = 32 * ks + 8 * g;
;             bf16x8 id;
; #pragma unroll
;             for (int j = 0; j < 8; ++j) id[j] = (k0 + j == n) ? (short)0x3F80 : (short)0;
; #pragma unroll
;             for (int mt = 0; mt < 2; ++mt) {
;                 Da[mt][nt] = __builtin_amdgcn_mfma_f32_16x16x32_bf16(Af[mt][ks], fa[nt][ks], Da[mt][nt], 0, 0, 0);
;                 Di[mt][nt] = __builtin_amdgcn_mfma_f32_16x16x32_bf16(Af[mt][ks], fi[nt][ks], Di[mt][nt], 0, 0, 0);
;                 Du[mt][nt] = __builtin_amdgcn_mfma_f32_16x16x32_bf16(Af[mt][ks], id, Du[mt][nt], 0, 0, 0);
;             }
;         }
;     }
	v_mfma_f32_16x16x32_bf16 v[140:143], v[18:21], v[78:81], 0
	v_cndmask_b32_e32 v51, 0, v205, vcc
	v_cmp_eq_u32_e32 vcc, v36, v107
	v_mul_f32_e32 v66, 0xbfb8aa3b, v66
	v_add_f32_e32 v67, v112, v67
	v_cndmask_b32_e32 v114, 0, v205, vcc
	v_cmp_eq_u32_e32 vcc, v35, v107
	v_add_f32_e32 v72, v113, v72
	v_mul_f32_e32 v67, 0xbfb8aa3b, v67
	v_cndmask_b32_e32 v115, 0, v205, vcc
	v_cmp_eq_u32_e32 vcc, v36, v110
	v_mul_f32_e32 v72, 0xbfb8aa3b, v72
	v_exp_f32_e32 v67, v67
	v_cndmask_b32_e32 v130, 0, v205, vcc
	v_cmp_eq_u32_e32 vcc, v35, v110
	v_exp_f32_e32 v72, v72
	v_add_f32_e32 v68, v112, v68
	v_cndmask_b32_e32 v136, 0, v205, vcc
	v_cmp_eq_u32_e32 vcc, v118, v125
	v_add_f32_e32 v67, 1.0, v67
	v_mul_f32_e32 v68, 0xbfb8aa3b, v68
	v_cndmask_b32_e32 v36, 0, v205, vcc
	v_cmp_eq_u32_e32 vcc, v119, v125
	v_add_f32_e32 v72, 1.0, v72
	v_rcp_f32_e32 v67, v67
	v_cndmask_b32_e32 v35, 0, v205, vcc
	v_cmp_eq_u32_e32 vcc, v119, v105
	v_perm_b32 v35, v35, v37, s50
	v_exp_f32_e32 v68, v68
	v_cndmask_b32_e32 v53, 0, v205, vcc
	v_cmp_eq_u32_e32 vcc, v118, v105
	v_perm_b32 v51, v53, v51, s50
	v_rcp_f32_e32 v72, v72
	v_cndmask_b32_e32 v52, 0, v205, vcc
	v_cmp_eq_u32_e32 vcc, v119, v107
	v_add_f32_e32 v71, v113, v71
	v_mul_f32_e32 v71, 0xbfb8aa3b, v71
	v_cndmask_b32_e32 v116, 0, v205, vcc
	v_cmp_eq_u32_e32 vcc, v118, v107
	v_exp_f32_e32 v71, v71
	v_add_f32_e32 v69, v112, v69
	v_cndmask_b32_e32 v117, 0, v205, vcc
	v_cmp_eq_u32_e32 vcc, v126, v125
	v_add_f32_e32 v71, 1.0, v71
	v_rcp_f32_e32 v71, v71
	v_cndmask_b32_e32 v37, 0, v205, vcc
	v_cmp_eq_u32_e32 vcc, v127, v125
	v_perm_b32 v37, v90, v37, s50
	v_mul_f32_e32 v69, 0xbfb8aa3b, v69
	v_cndmask_b32_e32 v38, 0, v205, vcc
	v_cmp_eq_u32_e32 vcc, v126, v105
	v_perm_b32 v36, v38, v36, s50
	v_exp_f32_e32 v69, v69
	v_cndmask_b32_e32 v62, 0, v205, vcc
	v_cmp_eq_u32_e32 vcc, v127, v105
	v_perm_b32 v53, v92, v62, s50
	v_mfma_f32_16x16x32_bf16 v[38:41], v[10:13], v[34:37], 0
	v_cndmask_b32_e32 v63, 0, v205, vcc
	v_cmp_eq_u32_e32 vcc, v126, v107
	v_perm_b32 v52, v63, v52, s50
	v_mfma_f32_16x16x32_bf16 v[34:37], v[18:21], v[34:37], 0
	v_cndmask_b32_e32 v90, 0, v205, vcc
	v_cmp_eq_u32_e32 vcc, v127, v107
	v_perm_b32 v93, v93, v90, s50
	v_perm_b32 v90, v114, v109, s50
	v_cndmask_b32_e32 v91, 0, v205, vcc
	v_cmp_eq_u32_e32 vcc, v119, v110
	v_perm_b32 v92, v91, v117, s50
	v_perm_b32 v91, v116, v115, s50
	v_cndmask_b32_e32 v109, 0, v205, vcc
	v_cmp_eq_u32_e32 vcc, v118, v110
	v_mfma_f32_16x16x32_bf16 v[114:117], v[10:13], v[90:93], 0
	s_nop 0
	v_cndmask_b32_e32 v132, 0, v205, vcc
	v_cmp_eq_u32_e32 vcc, v126, v110
	v_mfma_f32_16x16x32_bf16 v[118:121], v[18:21], v[90:93], 0
	s_nop 0
	v_cndmask_b32_e32 v90, 0, v205, vcc
	v_cmp_eq_u32_e32 vcc, v127, v110
	v_mfma_f32_16x16x32_bf16 v[126:129], v[10:13], v[30:33], 0
	s_nop 0
	v_cndmask_b32_e32 v91, 0, v205, vcc
	v_cmp_eq_u32_e32 vcc, v104, v110
	v_perm_b32 v92, v91, v132, s50
	v_perm_b32 v91, v109, v136, s50
	v_cndmask_b32_e32 v93, 0, v205, vcc
	v_cmp_eq_u32_e32 vcc, v102, v125
	v_add_u32_e32 v109, 39, v108
	v_mfma_f32_16x16x32_bf16 v[136:139], v[18:21], v[30:33], 0
	v_cndmask_b32_e32 v104, 0, v205, vcc
	v_cmp_eq_u32_e32 vcc, v109, v125
	v_perm_b32 v93, v93, v90, s50
	v_perm_b32 v90, v130, v111, s50
	v_cndmask_b32_e32 v30, 0, v205, vcc
	v_cmp_eq_u32_e32 vcc, v102, v105
	v_mfma_f32_16x16x32_bf16 v[132:135], v[10:13], v[78:81], 0
	s_nop 0
	v_cndmask_b32_e32 v111, 0, v205, vcc
	v_cmp_eq_u32_e32 vcc, v109, v105
	v_mfma_f32_16x16x32_bf16 v[62:65], v[10:13], v[50:53], 0
	s_nop 0
	v_cndmask_b32_e32 v78, 0, v205, vcc
	v_cmp_eq_u32_e32 vcc, v109, v107
	v_mfma_f32_16x16x32_bf16 v[50:53], v[18:21], v[50:53], 0
	s_nop 0
	v_cndmask_b32_e32 v130, 0, v205, vcc
	v_cmp_eq_u32_e32 vcc, v102, v110
	v_mfma_f32_16x16x32_bf16 v[144:147], v[18:21], v[90:93], 0
	v_add_u32_e32 v19, 33, v108
	v_cndmask_b32_e32 v152, 0, v205, vcc
	v_add_u32_e32 v20, 34, v108
	v_cmp_eq_u32_e32 vcc, v19, v125
	v_mfma_f32_16x16x32_bf16 v[10:13], v[10:13], v[90:93], 0
	v_add_u32_e32 v108, 38, v108
	v_cndmask_b32_e32 v21, 0, v205, vcc
	v_cmp_eq_u32_e32 vcc, v20, v125
	s_nop 1
	v_cndmask_b32_e32 v31, 0, v205, vcc
	v_cmp_eq_u32_e32 vcc, v19, v105
	s_nop 1
	v_cndmask_b32_e32 v79, 0, v205, vcc
	v_cmp_eq_u32_e32 vcc, v20, v105
	s_nop 1
	v_cndmask_b32_e32 v80, 0, v205, vcc
	v_cmp_eq_u32_e32 vcc, v20, v107
	s_nop 1
	v_cndmask_b32_e32 v81, 0, v205, vcc
	v_cmp_eq_u32_e32 vcc, v19, v107
	s_nop 1
	v_cndmask_b32_e32 v18, 0, v205, vcc
	v_cmp_eq_u32_e32 vcc, v19, v110
	v_perm_b32 v18, v18, v103, s50
	s_nop 0
	v_cndmask_b32_e32 v153, 0, v205, vcc
	v_cmp_eq_u32_e32 vcc, v20, v110
	s_nop 1
	v_cndmask_b32_e32 v154, 0, v205, vcc
	v_cmp_eq_u32_e32 vcc, v155, v125
	s_nop 1
	v_cndmask_b32_e32 v19, 0, v205, vcc
	v_cmp_eq_u32_e32 vcc, v156, v125
	v_perm_b32 v31, v19, v31, s50
	s_nop 0
	v_cndmask_b32_e32 v20, 0, v205, vcc
	v_cmp_eq_u32_e32 vcc, v155, v105
	s_nop 1
	v_cndmask_b32_e32 v90, 0, v205, vcc
	v_cmp_eq_u32_e32 vcc, v156, v105
	s_nop 1
	v_cndmask_b32_e32 v91, 0, v205, vcc
	v_cmp_eq_u32_e32 vcc, v156, v107
	s_nop 1
	v_cndmask_b32_e32 v157, 0, v205, vcc
	v_cmp_eq_u32_e32 vcc, v155, v107
	s_nop 1
	v_cndmask_b32_e32 v158, 0, v205, vcc
	v_cmp_eq_u32_e32 vcc, v159, v125
	s_nop 1
	v_cndmask_b32_e32 v32, 0, v205, vcc
	v_cmp_eq_u32_e32 vcc, v108, v125
	v_perm_b32 v32, v32, v20, s50
	s_nop 0
	v_cndmask_b32_e32 v33, 0, v205, vcc
	v_cmp_eq_u32_e32 vcc, v159, v105
	v_perm_b32 v33, v30, v33, s50
	v_perm_b32 v30, v21, v104, s50
	v_cndmask_b32_e32 v19, 0, v205, vcc
	v_cmp_eq_u32_e32 vcc, v108, v105
	v_mfma_f32_16x16x32_bf16 v[148:151], v[74:77], v[30:33], v[38:41]
	s_nop 0
	v_cndmask_b32_e32 v20, 0, v205, vcc
	v_cmp_eq_u32_e32 vcc, v108, v107
; template <bool FINAL, bool SMP>
; __device__ __forceinline__ void lru_unit(const Args& args, int l, int p, int h, LAS unsigned char* lds, int wave, int lane) {
;     ...
;     f32x4 Da[2][4], Di[2][4], Du[2][4];
; #pragma unroll
;     for (int nt = 0; nt < 4; ++nt) {
; #pragma unroll
;         for (int mt = 0; mt < 2; ++mt) { Da[mt][nt] = (f32x4){0.f, 0.f, 0.f, 0.f}; Di[mt][nt] = Da[mt][nt]; Du[mt][nt] = Da[mt][nt]; }
; #pragma unroll
;         for (int ks = 0; ks < 2; ++ks) {
;             const int n = 16 * nt + r16, k0 = 32 * ks + 8 * g;
;             bf16x8 id;
; #pragma unroll
;             for (int j = 0; j < 8; ++j) id[j] = (k0 + j == n) ? (short)0x3F80 : (short)0;
; #pragma unroll
;             for (int mt = 0; mt < 2; ++mt) {
;                 Da[mt][nt] = __builtin_amdgcn_mfma_f32_16x16x32_bf16(Af[mt][ks], fa[nt][ks], Da[mt][nt], 0, 0, 0);
;                 Di[mt][nt] = __builtin_amdgcn_mfma_f32_16x16x32_bf16(Af[mt][ks], fi[nt][ks], Di[mt][nt], 0, 0, 0);
;                 Du[mt][nt] = __builtin_amdgcn_mfma_f32_16x16x32_bf16(Af[mt][ks], id, Du[mt][nt], 0, 0, 0);
;             }
;         }
;     }
;     float totA[4], totB[4];
; #pragma unroll
;     for (int nt = 0; nt < 4; ++nt) {
;         const float c8 = lamv[nt];
;         float cA = 1.f, cB = 0.f;
; #pragma unroll
;         for (int mt = 0; mt < 2; ++mt) {
;             float av[4], bv[4];
; #pragma unroll
;             for (int j = 0; j < 4; ++j) {
;                 const float r = fsigmoid(Da[mt][nt][j] + bav[nt]), ig = fsigmoid(Di[mt][nt][j] + biv[nt]);
;                 const float a = __builtin_amdgcn_exp2f(-LOG2E * c8 * r);
;                 av[j] = a; bv[j] = __builtin_amdgcn_sqrtf(fmaxf(1.0f - a * a, 0.f)) * (ig * Du[mt][nt][j]);
;             }
;             float pA[4], pB[4];
;             pA[0] = av[0]; pB[0] = bv[0];
; #pragma unroll
;             for (int j = 1; j < 4; ++j) { pA[j] = pA[j - 1] * av[j]; pB[j] = av[j] * pB[j - 1] + bv[j]; }
;             float tA[4], tB[4];
; #pragma unroll
;             for (int gg = 0; gg < 4; ++gg) { tA[gg] = __shfl(pA[3], r16 + 16 * gg); tB[gg] = __shfl(pB[3], r16 + 16 * gg); }
;             float eA = cA, eB = cB;
; #pragma unroll
;             for (int gg = 0; gg < 3; ++gg) { const bool on = gg < g; const float nB = tA[gg] * eB + tB[gg], nA = eA * tA[gg]; eB = on ? nB : eB; eA = on ? nA : eA; }
; #pragma unroll
	v_mfma_f32_16x16x32_bf16 v[102:105], v[94:97], v[30:33], v[34:37]
	v_perm_b32 v33, v78, v20, s50
	v_cndmask_b32_e32 v21, 0, v205, vcc
	v_cmp_eq_u32_e32 vcc, v159, v107
	v_perm_b32 v32, v19, v91, s50
	v_perm_b32 v31, v90, v80, s50
	v_perm_b32 v30, v79, v111, s50
	v_cndmask_b32_e32 v20, 0, v205, vcc
	v_cmp_eq_u32_e32 vcc, v155, v110
	v_mfma_f32_16x16x32_bf16 v[90:93], v[74:77], v[30:33], v[62:65]
	v_perm_b32 v19, v158, v81, s50
	v_perm_b32 v20, v20, v157, s50
	v_perm_b32 v21, v130, v21, s50
	v_mfma_f32_16x16x32_bf16 v[78:81], v[94:97], v[30:33], v[50:53]
	v_cndmask_b32_e32 v30, 0, v205, vcc
	v_cmp_eq_u32_e32 vcc, v156, v110
	v_mfma_f32_16x16x32_bf16 v[62:65], v[74:77], v[18:21], v[114:117]
	s_nop 0
	v_cndmask_b32_e32 v31, 0, v205, vcc
	v_cmp_eq_u32_e32 vcc, v159, v110
	v_mfma_f32_16x16x32_bf16 v[50:53], v[94:97], v[18:21], v[118:121]
	s_nop 0
	v_cndmask_b32_e32 v18, 0, v205, vcc
	v_cmp_eq_u32_e32 vcc, v108, v110
	v_perm_b32 v116, v18, v31, s50
	v_perm_b32 v115, v30, v154, s50
	v_cndmask_b32_e32 v19, 0, v205, vcc
	v_cmp_eq_u32_e32 vcc, v109, v110
	v_perm_b32 v114, v153, v152, s50
	v_mfma_f32_16x16x32_bf16 v[38:41], v[74:77], v[98:101], v[126:129]
	v_cndmask_b32_e32 v20, 0, v205, vcc
	v_perm_b32 v117, v20, v19, s50
	global_load_dword v111, v122, s[16:17] offset:64
	global_load_dword v118, v122, s[36:37] offset:64
	global_load_dword v110, v122, s[16:17] offset:128
	global_load_dword v109, v122, s[36:37] offset:128
	global_load_dword v107, v122, s[36:37] offset:192
	global_load_dword v108, v122, s[16:17] offset:192
	v_mfma_f32_16x16x32_bf16 v[30:33], v[74:77], v[114:117], v[10:13]
	v_cmp_gt_u32_e32 vcc, 16, v106
	s_waitcnt vmcnt(5)
	v_add_f32_e32 v46, v111, v46
	v_add_f32_e32 v10, v113, v86
	v_mul_f32_e32 v10, 0xbfb8aa3b, v10
	v_mfma_f32_16x16x32_bf16 v[34:37], v[74:77], v[14:17], v[132:135]
	v_exp_f32_e32 v74, v10
	v_add_f32_e32 v75, v112, v82
	v_mul_f32_e32 v75, 0xbfb8aa3b, v75
	v_mfma_f32_16x16x32_bf16 v[18:21], v[94:97], v[98:101], v[136:139]
	v_add_f32_e32 v74, 1.0, v74
	v_rcp_f32_e32 v74, v74
	v_exp_f32_e32 v75, v75
	v_mfma_f32_16x16x32_bf16 v[14:17], v[94:97], v[14:17], v[140:143]
	global_load_dword v99, v122, s[62:63] offset:64
	global_load_dword v100, v122, s[62:63] offset:128
	global_load_dword v98, v122, s[62:63] offset:192
	v_add_f32_e32 v77, v113, v87
	v_add_f32_e32 v75, 1.0, v75
	v_mfma_f32_16x16x32_bf16 v[10:13], v[94:97], v[114:117], v[144:147]
	v_mul_f32_e32 v94, 0xbfb8aa3b, v123
	v_mul_f32_e32 v74, v94, v74
	v_exp_f32_e32 v74, v74
	v_rcp_f32_e32 v75, v75
	v_mul_f32_e32 v77, 0xbfb8aa3b, v77
	v_exp_f32_e32 v77, v77
	v_fma_f32 v76, -v74, v74, 1.0
	v_max_f32_e32 v76, 0, v76
	v_sqrt_f32_e32 v76, v76
	v_mul_f32_e32 v75, v148, v75
	v_add_f32_e32 v77, 1.0, v77
	v_rcp_f32_e32 v77, v77
	v_mul_f32_e32 v212, v75, v76
	v_add_f32_e32 v75, 1.0, v83
	v_rcp_f32_e32 v75, v75
	v_add_f32_e32 v83, v113, v88
	v_mul_f32_e32 v83, 0xbfb8aa3b, v83
	v_exp_f32_e32 v83, v83
	v_mul_f32_e32 v86, v149, v75
	v_add_f32_e32 v75, 1.0, v84
	v_add_f32_e32 v84, v113, v89
	v_mul_f32_e32 v84, 0xbfb8aa3b, v84
	v_exp_f32_e32 v84, v84
	v_add_f32_e32 v83, 1.0, v83
	v_rcp_f32_e32 v83, v83
	v_mul_f32_e32 v77, v94, v77
	v_add_f32_e32 v84, 1.0, v84
	v_rcp_f32_e32 v84, v84
	v_exp_f32_e32 v77, v77
	v_mul_f32_e32 v83, v94, v83
	v_exp_f32_e32 v83, v83
	v_rcp_f32_e32 v75, v75
	v_mul_f32_e32 v84, v94, v84
	v_fma_f32 v76, -v77, v77, 1.0
	v_exp_f32_e32 v84, v84
	v_max_f32_e32 v76, 0, v76
	v_sqrt_f32_e32 v76, v76
	v_fma_f32 v87, -v83, v83, 1.0
	v_max_f32_e32 v87, 0, v87
	v_mul_f32_e32 v88, v150, v75
	v_add_f32_e32 v75, 1.0, v85
	v_sqrt_f32_e32 v87, v87
	v_rcp_f32_e32 v75, v75
	v_fma_f32 v85, -v84, v84, 1.0
	v_max_f32_e32 v85, 0, v85
	v_mul_f32_e32 v127, v77, v212
	v_sqrt_f32_e32 v85, v85
	v_fmac_f32_e32 v127, v86, v76
	v_mul_f32_e32 v126, v83, v127
	v_mul_f32_e32 v89, v151, v75
	v_mul_f32_e32 v75, v74, v77
	v_fmac_f32_e32 v126, v88, v87
	v_and_or_b32 v82, v204, 64, v125
	v_mul_f32_e32 v76, v83, v75
	v_mul_f32_e32 v123, v84, v126
	v_mul_f32_e32 v77, v84, v76
	v_fmac_f32_e32 v123, v89, v85
	v_lshlrev_b32_e32 v95, 2, v82
	ds_bpermute_b32 v87, v95, v77
	ds_bpermute_b32 v88, v95, v123
	ds_bpermute_b32 v86, v95, v77 offset:64
	ds_bpermute_b32 v85, v95, v123 offset:64
	ds_bpermute_b32 v84, v95, v77 offset:128
	ds_bpermute_b32 v83, v95, v123 offset:128
	ds_bpermute_b32 v89, v95, v77 offset:192
	ds_bpermute_b32 v82, v95, v123 offset:192
	s_waitcnt lgkmcnt(6)
	v_fmac_f32_e32 v88, 0, v87
	s_waitcnt lgkmcnt(4)
	v_fma_f32 v96, v88, v86, v85
	s_waitcnt lgkmcnt(2)
	v_fma_f32 v96, v96, v84, v83
	v_mul_f32_e32 v97, v87, v86
	s_waitcnt lgkmcnt(0)
	v_fmac_f32_e32 v82, v96, v89
	v_exp_f32_e32 v96, v66
	v_mul_f32_e32 v66, v94, v70
	v_exp_f32_e32 v66, v66
	v_mul_f32_e32 v97, v97, v84
	v_mul_f32_e32 v70, v97, v89
	v_add_f32_e32 v89, 1.0, v96
	v_fma_f32 v96, -v66, v66, 1.0
	v_rcp_f32_e32 v89, v89
	v_max_f32_e32 v96, 0, v96
	v_sqrt_f32_e32 v96, v96
	v_mul_f32_e32 v71, v94, v71
	v_mul_f32_e32 v89, v102, v89
	v_exp_f32_e32 v71, v71
	v_mul_f32_e32 v130, v89, v96
	v_mul_f32_e32 v96, v103, v67
	v_add_f32_e32 v67, 1.0, v68
	v_mul_f32_e32 v68, v94, v72
	v_exp_f32_e32 v72, v68
	v_add_f32_e32 v68, v113, v73
	v_mul_f32_e32 v68, 0xbfb8aa3b, v68
	v_exp_f32_e32 v68, v68
	v_fma_f32 v89, -v71, v71, 1.0
	v_rcp_f32_e32 v67, v67
	v_max_f32_e32 v89, 0, v89
	v_add_f32_e32 v68, 1.0, v68
	v_rcp_f32_e32 v68, v68
	v_sqrt_f32_e32 v89, v89
	v_fma_f32 v73, -v72, v72, 1.0
	v_max_f32_e32 v73, 0, v73
	v_mul_f32_e32 v68, v94, v68
	v_exp_f32_e32 v94, v68
	v_sqrt_f32_e32 v73, v73
	v_mul_f32_e32 v97, v104, v67
	v_add_f32_e32 v67, 1.0, v69
	v_fma_f32 v68, -v94, v94, 1.0
	v_mul_f32_e32 v46, 0xbfb8aa3b, v46
	v_rcp_f32_e32 v67, v67
	v_max_f32_e32 v68, 0, v68
	v_mul_f32_e32 v137, v71, v130
	v_exp_f32_e32 v46, v46
	v_sqrt_f32_e32 v101, v68
	v_fmac_f32_e32 v137, v96, v89
	v_mul_f32_e32 v136, v72, v137
	v_fmac_f32_e32 v136, v97, v73
	v_add_f32_e32 v58, v111, v58
	v_mul_f32_e32 v102, v105, v67
	v_mul_f32_e32 v135, v94, v136
	v_mul_f32_e32 v58, 0xbfb8aa3b, v58
	v_add_f32_e32 v46, 1.0, v46
	v_fmac_f32_e32 v135, v102, v101
	v_exp_f32_e32 v101, v58
	v_rcp_f32_e32 v46, v46
	s_waitcnt vmcnt(2)
; __device__ __forceinline__ float fsigmoid(float v) { return __builtin_amdgcn_rcpf(1.0f + __builtin_amdgcn_exp2f(-LOG2E * v)); }
; template <bool FINAL, bool SMP>
; __device__ __forceinline__ void lru_unit(const Args& args, int l, int p, int h, LAS unsigned char* lds, int wave, int lane) {
;     ...
;     float totA[4], totB[4];
; #pragma unroll
;     for (int nt = 0; nt < 4; ++nt) {
;         const float c8 = lamv[nt];
;         float cA = 1.f, cB = 0.f;
; #pragma unroll
;         for (int mt = 0; mt < 2; ++mt) {
;             float av[4], bv[4];
; #pragma unroll
;             for (int j = 0; j < 4; ++j) {
;                 const float r = fsigmoid(Da[mt][nt][j] + bav[nt]), ig = fsigmoid(Di[mt][nt][j] + biv[nt]);
;                 const float a = __builtin_amdgcn_exp2f(-LOG2E * c8 * r);
;                 av[j] = a; bv[j] = __builtin_amdgcn_sqrtf(fmaxf(1.0f - a * a, 0.f)) * (ig * Du[mt][nt][j]);
;             }
;             float pA[4], pB[4];
;             pA[0] = av[0]; pB[0] = bv[0];
; #pragma unroll
;             for (int j = 1; j < 4; ++j) { pA[j] = pA[j - 1] * av[j]; pB[j] = av[j] * pB[j - 1] + bv[j]; }
;             float tA[4], tB[4];
; #pragma unroll
;             for (int gg = 0; gg < 4; ++gg) { tA[gg] = __shfl(pA[3], r16 + 16 * gg); tB[gg] = __shfl(pB[3], r16 + 16 * gg); }
;             float eA = cA, eB = cB;
; #pragma unroll
;             for (int gg = 0; gg < 3; ++gg) { const bool on = gg < g; const float nB = tA[gg] * eB + tB[gg], nA = eA * tA[gg]; eB = on ? nB : eB; eA = on ? nA : eA; }
; #pragma unroll
;             for (int j = 0; j < 4; ++j) { Da[mt][nt][j] = eA * pA[j]; Di[mt][nt][j] = pA[j] * eB + pB[j]; }
; #pragma unroll
;             for (int gg = 0; gg < 4; ++gg) { cB = tA[gg] * cB + tB[gg]; cA = cA * tA[gg]; }
	v_mul_f32_e32 v99, 0xbfb8aa3b, v99
	v_add_f32_e32 v42, v118, v42
	v_add_f32_e32 v101, 1.0, v101
	v_add_f32_e32 v59, v111, v59
	v_mul_f32_e32 v42, 0xbfb8aa3b, v42
	v_mul_f32_e32 v46, v99, v46
	v_rcp_f32_e32 v101, v101
	v_mul_f32_e32 v59, 0xbfb8aa3b, v59
	v_exp_f32_e32 v42, v42
	v_exp_f32_e32 v145, v46
	v_mul_f32_e32 v67, v66, v71
	v_exp_f32_e32 v59, v59
	v_add_f32_e32 v60, v111, v60
	v_mul_f32_e32 v68, v72, v67
	v_add_f32_e32 v54, v118, v54
	v_mul_f32_e32 v60, 0xbfb8aa3b, v60
	v_mul_f32_e32 v69, v94, v68
	v_mul_f32_e32 v54, 0xbfb8aa3b, v54
	v_exp_f32_e32 v60, v60
	v_add_f32_e32 v61, v111, v61
	ds_bpermute_b32 v97, v95, v69
	ds_bpermute_b32 v94, v95, v135
	v_exp_f32_e32 v102, v54
	v_mul_f32_e32 v54, v99, v101
	v_mul_f32_e32 v61, 0xbfb8aa3b, v61
	v_add_f32_e32 v42, 1.0, v42
	v_fma_f32 v46, -v145, v145, 1.0
	v_exp_f32_e32 v129, v54
	v_add_f32_e32 v59, 1.0, v59
	v_exp_f32_e32 v61, v61
	v_rcp_f32_e32 v42, v42
	v_max_f32_e32 v46, 0, v46
	v_rcp_f32_e32 v59, v59
	v_add_f32_e32 v55, v118, v55
	v_sqrt_f32_e32 v46, v46
	v_mul_f32_e32 v55, 0xbfb8aa3b, v55
	v_add_f32_e32 v60, 1.0, v60
	v_exp_f32_e32 v55, v55
	v_add_f32_e32 v56, v118, v56
	v_rcp_f32_e32 v60, v60
	v_add_f32_e32 v47, v111, v47
	s_waitcnt lgkmcnt(0)
	v_fmac_f32_e32 v94, v82, v97
	v_mul_f32_e32 v54, v70, v97
	v_add_f32_e32 v97, 1.0, v102
	v_fma_f32 v101, -v129, v129, 1.0
	v_mul_f32_e32 v56, 0xbfb8aa3b, v56
	v_add_f32_e32 v61, 1.0, v61
	v_mul_f32_e32 v47, 0xbfb8aa3b, v47
	v_mul_f32_e32 v42, v78, v42
	v_rcp_f32_e32 v97, v97
	v_max_f32_e32 v101, 0, v101
	v_mul_f32_e32 v59, v99, v59
	v_exp_f32_e32 v56, v56
	v_rcp_f32_e32 v61, v61
	v_exp_f32_e32 v47, v47
	v_mul_f32_e32 v142, v42, v46
	v_add_f32_e32 v46, v111, v48
	v_sqrt_f32_e32 v101, v101
	v_exp_f32_e32 v59, v59
	v_mul_f32_e32 v46, 0xbfb8aa3b, v46
	v_add_f32_e32 v55, 1.0, v55
	v_mul_f32_e32 v60, v99, v60
	v_exp_f32_e32 v46, v46
	v_rcp_f32_e32 v55, v55
	v_exp_f32_e32 v60, v60
	v_add_f32_e32 v57, v118, v57
	v_mul_f32_e32 v90, v90, v97
	v_add_f32_e32 v56, 1.0, v56
	v_mul_f32_e32 v57, 0xbfb8aa3b, v57
	v_mul_f32_e32 v61, v99, v61
	v_add_f32_e32 v47, 1.0, v47
	v_mul_f32_e32 v128, v90, v101
	v_fma_f32 v90, -v59, v59, 1.0
	v_rcp_f32_e32 v56, v56
	v_exp_f32_e32 v57, v57
	v_exp_f32_e32 v61, v61
	v_rcp_f32_e32 v47, v47
	v_max_f32_e32 v90, 0, v90
	v_add_f32_e32 v46, 1.0, v46
	v_sqrt_f32_e32 v90, v90
	v_mul_f32_e32 v55, v91, v55
	v_fma_f32 v91, -v60, v60, 1.0
	v_rcp_f32_e32 v46, v46
	v_max_f32_e32 v91, 0, v91
	v_add_f32_e32 v43, v118, v43
	v_add_f32_e32 v48, v111, v49
	v_sqrt_f32_e32 v91, v91
	v_mul_f32_e32 v56, v92, v56
	v_add_f32_e32 v57, 1.0, v57
	v_fma_f32 v92, -v61, v61, 1.0
	v_mul_f32_e32 v43, 0xbfb8aa3b, v43
	v_mul_f32_e32 v47, v99, v47
	v_mul_f32_e32 v48, 0xbfb8aa3b, v48
	v_rcp_f32_e32 v57, v57
	v_max_f32_e32 v92, 0, v92
	v_mul_f32_e32 v134, v59, v128
	v_exp_f32_e32 v43, v43
	v_exp_f32_e32 v47, v47
	v_add_f32_e32 v44, v118, v44
	v_exp_f32_e32 v48, v48
	v_sqrt_f32_e32 v92, v92
	v_fmac_f32_e32 v134, v55, v90
	v_mul_f32_e32 v44, 0xbfb8aa3b, v44
	v_mul_f32_e32 v46, v99, v46
	v_mul_f32_e32 v133, v60, v134
	v_exp_f32_e32 v44, v44
	v_exp_f32_e32 v46, v46
	v_mul_f32_e32 v139, v129, v59
	v_fmac_f32_e32 v133, v56, v91
	v_mul_f32_e32 v57, v93, v57
	v_mul_f32_e32 v140, v60, v139
	v_mul_f32_e32 v132, v61, v133
	v_add_f32_e32 v42, 1.0, v43
	v_fma_f32 v43, -v47, v47, 1.0
	v_add_f32_e32 v48, 1.0, v48
	v_mul_f32_e32 v141, v61, v140
	v_fmac_f32_e32 v132, v57, v92
	v_rcp_f32_e32 v42, v42
	v_max_f32_e32 v43, 0, v43
	v_rcp_f32_e32 v48, v48
	ds_bpermute_b32 v150, v95, v141
	ds_bpermute_b32 v152, v95, v132
	v_sqrt_f32_e32 v43, v43
	v_add_f32_e32 v44, 1.0, v44
	v_fma_f32 v49, -v46, v46, 1.0
	ds_bpermute_b32 v148, v95, v141 offset:64
	ds_bpermute_b32 v149, v95, v132 offset:64
	v_rcp_f32_e32 v44, v44
	v_max_f32_e32 v49, 0, v49
	ds_bpermute_b32 v146, v95, v141 offset:128
	ds_bpermute_b32 v147, v95, v132 offset:128
	v_sqrt_f32_e32 v49, v49
	v_add_f32_e32 v45, v118, v45
	ds_bpermute_b32 v55, v95, v141 offset:192
	ds_bpermute_b32 v144, v95, v132 offset:192
	v_mul_f32_e32 v42, v79, v42
	v_mul_f32_e32 v45, 0xbfb8aa3b, v45
	v_mul_f32_e32 v48, v99, v48
	v_mul_f32_e32 v158, v47, v142
	v_exp_f32_e32 v45, v45
	v_exp_f32_e32 v48, v48
	v_fmac_f32_e32 v158, v42, v43
	v_add_f32_e32 v26, v110, v26
	s_waitcnt lgkmcnt(6)
	v_fmac_f32_e32 v152, 0, v150
	v_mul_f32_e32 v44, v80, v44
	v_mul_f32_e32 v157, v46, v158
	v_mul_f32_e32 v26, 0xbfb8aa3b, v26
	v_add_f32_e32 v6, v110, v6
	s_waitcnt lgkmcnt(4)
	v_fma_f32 v56, v152, v148, v149
	v_mul_f32_e32 v57, v150, v148
	v_fmac_f32_e32 v157, v44, v49
	v_exp_f32_e32 v44, v26
	v_mul_f32_e32 v6, 0xbfb8aa3b, v6
	s_waitcnt lgkmcnt(2)
	v_fma_f32 v56, v56, v146, v147
	v_mul_f32_e32 v57, v57, v146
	v_exp_f32_e32 v6, v6
	s_waitcnt lgkmcnt(0)
	v_fmac_f32_e32 v144, v56, v55
	v_mul_f32_e32 v156, v57, v55
	v_add_f32_e32 v45, 1.0, v45
	v_fma_f32 v55, -v48, v48, 1.0
	v_rcp_f32_e32 v45, v45
	v_max_f32_e32 v55, 0, v55
	v_sqrt_f32_e32 v55, v55
	v_add_f32_e32 v44, 1.0, v44
	v_add_f32_e32 v27, v110, v27
	v_rcp_f32_e32 v44, v44
	v_mul_f32_e32 v27, 0xbfb8aa3b, v27
	v_add_f32_e32 v6, 1.0, v6
	v_mul_f32_e32 v167, v145, v47
	v_exp_f32_e32 v27, v27
	v_add_f32_e32 v28, v110, v28
	v_rcp_f32_e32 v6, v6
	v_mul_f32_e32 v45, v81, v45
	v_mul_f32_e32 v168, v46, v167
	v_mul_f32_e32 v153, v48, v157
	v_mul_f32_e32 v28, 0xbfb8aa3b, v28
	v_mul_f32_e32 v169, v48, v168
	v_fmac_f32_e32 v153, v45, v55
	s_waitcnt vmcnt(1)
; __device__ __forceinline__ float fsigmoid(float v) { return __builtin_amdgcn_rcpf(1.0f + __builtin_amdgcn_exp2f(-LOG2E * v)); }
; template <bool FINAL, bool SMP>
; __device__ __forceinline__ void lru_unit(const Args& args, int l, int p, int h, LAS unsigned char* lds, int wave, int lane) {
;     ...
;     float totA[4], totB[4];
; #pragma unroll
;     for (int nt = 0; nt < 4; ++nt) {
;         const float c8 = lamv[nt];
;         float cA = 1.f, cB = 0.f;
; #pragma unroll
;         for (int mt = 0; mt < 2; ++mt) {
;             float av[4], bv[4];
; #pragma unroll
;             for (int j = 0; j < 4; ++j) {
;                 const float r = fsigmoid(Da[mt][nt][j] + bav[nt]), ig = fsigmoid(Di[mt][nt][j] + biv[nt]);
;                 const float a = __builtin_amdgcn_exp2f(-LOG2E * c8 * r);
;                 av[j] = a; bv[j] = __builtin_amdgcn_sqrtf(fmaxf(1.0f - a * a, 0.f)) * (ig * Du[mt][nt][j]);
;             }
;             float pA[4], pB[4];
;             pA[0] = av[0]; pB[0] = bv[0];
; #pragma unroll
;             for (int j = 1; j < 4; ++j) { pA[j] = pA[j - 1] * av[j]; pB[j] = av[j] * pB[j - 1] + bv[j]; }
;             float tA[4], tB[4];
; #pragma unroll
;             for (int gg = 0; gg < 4; ++gg) { tA[gg] = __shfl(pA[3], r16 + 16 * gg); tB[gg] = __shfl(pB[3], r16 + 16 * gg); }
;             float eA = cA, eB = cB;
; #pragma unroll
;             for (int gg = 0; gg < 3; ++gg) { const bool on = gg < g; const float nB = tA[gg] * eB + tB[gg], nA = eA * tA[gg]; eB = on ? nB : eB; eA = on ? nA : eA; }
; #pragma unroll
;             for (int j = 0; j < 4; ++j) { Da[mt][nt][j] = eA * pA[j]; Di[mt][nt][j] = pA[j] * eB + pB[j]; }
; #pragma unroll
;             for (int gg = 0; gg < 4; ++gg) { cB = tA[gg] * cB + tB[gg]; cA = cA * tA[gg]; }
	v_mul_f32_e32 v45, 0xbfb8aa3b, v100
	v_add_f32_e32 v22, v109, v22
	v_exp_f32_e32 v28, v28
	v_add_f32_e32 v29, v110, v29
	ds_bpermute_b32 v43, v95, v169
	ds_bpermute_b32 v186, v95, v153
	v_mul_f32_e32 v22, 0xbfb8aa3b, v22
	v_mul_f32_e32 v44, v45, v44
	v_mul_f32_e32 v29, 0xbfb8aa3b, v29
	v_add_f32_e32 v2, v109, v2
	v_exp_f32_e32 v22, v22
	v_exp_f32_e32 v143, v44
	v_add_f32_e32 v27, 1.0, v27
	v_exp_f32_e32 v29, v29
	v_mul_f32_e32 v2, 0xbfb8aa3b, v2
	v_mul_f32_e32 v6, v45, v6
	v_rcp_f32_e32 v27, v27
	v_exp_f32_e32 v2, v2
	v_exp_f32_e32 v172, v6
	v_add_f32_e32 v28, 1.0, v28
	v_rcp_f32_e32 v28, v28
	s_waitcnt lgkmcnt(0)
	v_fmac_f32_e32 v186, v144, v43
	v_mul_f32_e32 v192, v156, v43
	v_add_f32_e32 v22, 1.0, v22
	v_fma_f32 v43, -v143, v143, 1.0
	v_add_f32_e32 v23, v109, v23
	v_add_f32_e32 v29, 1.0, v29
	v_rcp_f32_e32 v22, v22
	v_max_f32_e32 v43, 0, v43
	v_mul_f32_e32 v23, 0xbfb8aa3b, v23
	v_mul_f32_e32 v27, v45, v27
	v_rcp_f32_e32 v29, v29
	v_add_f32_e32 v2, 1.0, v2
	v_fma_f32 v6, -v172, v172, 1.0
	v_sqrt_f32_e32 v43, v43
	v_exp_f32_e32 v23, v23
	v_exp_f32_e32 v27, v27
	v_add_f32_e32 v24, v109, v24
	v_rcp_f32_e32 v2, v2
	v_max_f32_e32 v6, 0, v6
	v_mul_f32_e32 v24, 0xbfb8aa3b, v24
	v_mul_f32_e32 v28, v45, v28
	v_sqrt_f32_e32 v6, v6
	v_exp_f32_e32 v24, v24
	v_exp_f32_e32 v28, v28
	v_add_f32_e32 v25, v109, v25
	v_mul_f32_e32 v22, v62, v22
	v_mul_f32_e32 v25, 0xbfb8aa3b, v25
	v_mul_f32_e32 v29, v45, v29
	v_add_f32_e32 v7, v110, v7
	v_mul_f32_e32 v138, v22, v43
	v_add_f32_e32 v22, 1.0, v23
	v_fma_f32 v23, -v27, v27, 1.0
	v_exp_f32_e32 v25, v25
	v_exp_f32_e32 v29, v29
	v_mul_f32_e32 v7, 0xbfb8aa3b, v7
	v_mul_f32_e32 v2, v50, v2
	v_rcp_f32_e32 v22, v22
	v_max_f32_e32 v23, 0, v23
	v_exp_f32_e32 v7, v7
	v_mul_f32_e32 v164, v2, v6
	v_add_f32_e32 v6, v110, v8
	v_sqrt_f32_e32 v23, v23
	v_add_f32_e32 v24, 1.0, v24
	v_fma_f32 v43, -v28, v28, 1.0
	v_mul_f32_e32 v6, 0xbfb8aa3b, v6
	v_rcp_f32_e32 v24, v24
	v_max_f32_e32 v43, 0, v43
	v_exp_f32_e32 v6, v6
	v_add_f32_e32 v8, v110, v9
	v_sqrt_f32_e32 v43, v43
	v_add_f32_e32 v25, 1.0, v25
	v_fma_f32 v44, -v29, v29, 1.0
	v_mul_f32_e32 v8, 0xbfb8aa3b, v8
	v_mul_f32_e32 v22, v63, v22
	v_rcp_f32_e32 v25, v25
	v_max_f32_e32 v44, 0, v44
	v_mul_f32_e32 v155, v27, v138
	v_add_f32_e32 v7, 1.0, v7
	v_exp_f32_e32 v8, v8
	v_sqrt_f32_e32 v44, v44
	v_fmac_f32_e32 v155, v22, v23
	v_rcp_f32_e32 v7, v7
	v_mul_f32_e32 v24, v64, v24
	v_mul_f32_e32 v154, v28, v155
	v_add_f32_e32 v6, 1.0, v6
	v_mul_f32_e32 v161, v143, v27
	v_fmac_f32_e32 v154, v24, v43
	v_rcp_f32_e32 v6, v6
	v_mul_f32_e32 v25, v65, v25
	v_mul_f32_e32 v162, v28, v161
	v_mul_f32_e32 v151, v29, v154
	v_add_f32_e32 v3, v109, v3
	v_add_f32_e32 v8, 1.0, v8
	v_mul_f32_e32 v163, v29, v162
	v_fmac_f32_e32 v151, v25, v44
	v_mul_f32_e32 v3, 0xbfb8aa3b, v3
	v_mul_f32_e32 v7, v45, v7
	v_rcp_f32_e32 v8, v8
	ds_bpermute_b32 v177, v95, v163
	ds_bpermute_b32 v178, v95, v151
	v_exp_f32_e32 v3, v3
	v_exp_f32_e32 v7, v7
	v_add_f32_e32 v4, v109, v4
	ds_bpermute_b32 v175, v95, v163 offset:64
	ds_bpermute_b32 v176, v95, v151 offset:64
	v_mul_f32_e32 v4, 0xbfb8aa3b, v4
	v_mul_f32_e32 v6, v45, v6
	ds_bpermute_b32 v173, v95, v163 offset:128
	ds_bpermute_b32 v174, v95, v151 offset:128
	v_exp_f32_e32 v4, v4
	v_exp_f32_e32 v6, v6
	v_add_f32_e32 v5, v109, v5
	ds_bpermute_b32 v22, v95, v163 offset:192
	ds_bpermute_b32 v165, v95, v151 offset:192
	v_mul_f32_e32 v5, 0xbfb8aa3b, v5
	v_mul_f32_e32 v8, v45, v8
	v_add_f32_e32 v2, 1.0, v3
	v_fma_f32 v3, -v7, v7, 1.0
	v_exp_f32_e32 v5, v5
	v_exp_f32_e32 v8, v8
	s_waitcnt lgkmcnt(6)
	v_fmac_f32_e32 v178, 0, v177
	v_rcp_f32_e32 v2, v2
	v_max_f32_e32 v3, 0, v3
	s_waitcnt lgkmcnt(4)
	v_fma_f32 v23, v178, v175, v176
	v_mul_f32_e32 v24, v177, v175
	v_sqrt_f32_e32 v3, v3
	v_add_f32_e32 v4, 1.0, v4
	v_fma_f32 v9, -v6, v6, 1.0
	s_waitcnt lgkmcnt(2)
	v_fma_f32 v23, v23, v173, v174
	v_mul_f32_e32 v24, v24, v173
	v_rcp_f32_e32 v4, v4
	v_max_f32_e32 v9, 0, v9
	s_waitcnt lgkmcnt(0)
	v_fmac_f32_e32 v165, v23, v22
	v_mul_f32_e32 v180, v24, v22
	v_sqrt_f32_e32 v9, v9
	v_add_f32_e32 v5, 1.0, v5
	v_fma_f32 v22, -v8, v8, 1.0
	v_mul_f32_e32 v2, v51, v2
	v_rcp_f32_e32 v5, v5
	v_max_f32_e32 v22, 0, v22
	v_mul_f32_e32 v187, v7, v164
	v_sqrt_f32_e32 v22, v22
	v_fmac_f32_e32 v187, v2, v3
	v_mul_f32_e32 v4, v52, v4
	v_mul_f32_e32 v185, v6, v187
	v_fmac_f32_e32 v185, v4, v9
	v_add_f32_e32 v2, v108, v38
	v_mul_f32_e32 v5, v53, v5
	v_mul_f32_e32 v179, v8, v185
	v_mul_f32_e32 v2, 0xbfb8aa3b, v2
	v_fmac_f32_e32 v179, v5, v22
	v_exp_f32_e32 v5, v2
	v_mul_f32_e32 v200, v172, v7
	v_mul_f32_e32 v202, v6, v200
	v_mul_f32_e32 v211, v8, v202
	v_add_f32_e32 v5, 1.0, v5
	v_rcp_f32_e32 v5, v5
	s_waitcnt vmcnt(0)
	v_mul_f32_e32 v6, 0xbfb8aa3b, v98
	v_add_f32_e32 v7, v107, v34
	ds_bpermute_b32 v4, v95, v211
	ds_bpermute_b32 v219, v95, v179
	v_mul_f32_e32 v7, 0xbfb8aa3b, v7
	v_mul_f32_e32 v5, v6, v5
	v_exp_f32_e32 v7, v7
	v_exp_f32_e32 v160, v5
	s_waitcnt lgkmcnt(0)
; __device__ __forceinline__ float fsigmoid(float v) { return __builtin_amdgcn_rcpf(1.0f + __builtin_amdgcn_exp2f(-LOG2E * v)); }
; template <bool FINAL, bool SMP>
; __device__ __forceinline__ void lru_unit(const Args& args, int l, int p, int h, LAS unsigned char* lds, int wave, int lane) {
;     ...
;     float totA[4], totB[4];
; #pragma unroll
;     for (int nt = 0; nt < 4; ++nt) {
;         const float c8 = lamv[nt];
;         float cA = 1.f, cB = 0.f;
; #pragma unroll
;         for (int mt = 0; mt < 2; ++mt) {
;             float av[4], bv[4];
; #pragma unroll
;             for (int j = 0; j < 4; ++j) {
;                 const float r = fsigmoid(Da[mt][nt][j] + bav[nt]), ig = fsigmoid(Di[mt][nt][j] + biv[nt]);
;                 const float a = __builtin_amdgcn_exp2f(-LOG2E * c8 * r);
;                 av[j] = a; bv[j] = __builtin_amdgcn_sqrtf(fmaxf(1.0f - a * a, 0.f)) * (ig * Du[mt][nt][j]);
;             }
;             float pA[4], pB[4];
;             pA[0] = av[0]; pB[0] = bv[0];
; #pragma unroll
;             for (int j = 1; j < 4; ++j) { pA[j] = pA[j - 1] * av[j]; pB[j] = av[j] * pB[j - 1] + bv[j]; }
;             float tA[4], tB[4];
; #pragma unroll
;             for (int gg = 0; gg < 4; ++gg) { tA[gg] = __shfl(pA[3], r16 + 16 * gg); tB[gg] = __shfl(pB[3], r16 + 16 * gg); }
;             float eA = cA, eB = cB;
; #pragma unroll
;             for (int gg = 0; gg < 3; ++gg) { const bool on = gg < g; const float nB = tA[gg] * eB + tB[gg], nA = eA * tA[gg]; eB = on ? nB : eB; eA = on ? nA : eA; }
; #pragma unroll
;             for (int j = 0; j < 4; ++j) { Da[mt][nt][j] = eA * pA[j]; Di[mt][nt][j] = pA[j] * eB + pB[j]; }
; #pragma unroll
;             for (int gg = 0; gg < 4; ++gg) { cB = tA[gg] * cB + tB[gg]; cA = cA * tA[gg]; }
;         }
;         totA[nt] = cA; totB[nt] = cB;
;     ...
;         if (g == 0) {
; #pragma unroll
;             for (int nt = 0; nt < 4; ++nt) { WA[wave * 64 + 16 * nt + r16] = totA[nt]; WB[wave * 64 + 16 * nt + r16] = totB[nt]; }
;         }
	v_fmac_f32_e32 v219, v165, v4
	v_mul_f32_e32 v220, v180, v4
	v_add_f32_e32 v4, 1.0, v7
	v_fma_f32 v5, -v160, v160, 1.0
	v_add_f32_e32 v8, v107, v35
	v_rcp_f32_e32 v4, v4
	v_max_f32_e32 v5, 0, v5
	v_mul_f32_e32 v8, 0xbfb8aa3b, v8
	v_sqrt_f32_e32 v5, v5
	v_exp_f32_e32 v8, v8
	v_add_f32_e32 v7, v108, v39
	v_mul_f32_e32 v7, 0xbfb8aa3b, v7
	v_mul_f32_e32 v4, v30, v4
	v_exp_f32_e32 v7, v7
	v_mul_f32_e32 v159, v4, v5
	v_add_f32_e32 v4, 1.0, v8
	v_add_f32_e32 v8, v108, v40
	v_mul_f32_e32 v8, 0xbfb8aa3b, v8
	v_exp_f32_e32 v8, v8
	v_add_f32_e32 v22, v108, v41
	v_mul_f32_e32 v22, 0xbfb8aa3b, v22
	v_add_f32_e32 v7, 1.0, v7
	v_exp_f32_e32 v22, v22
	v_rcp_f32_e32 v7, v7
	v_add_f32_e32 v8, 1.0, v8
	v_rcp_f32_e32 v8, v8
	v_add_f32_e32 v22, 1.0, v22
	v_mul_f32_e32 v7, v6, v7
	v_rcp_f32_e32 v22, v22
	v_exp_f32_e32 v7, v7
	v_add_f32_e32 v9, v107, v36
	v_mul_f32_e32 v9, 0xbfb8aa3b, v9
	v_mul_f32_e32 v8, v6, v8
	v_exp_f32_e32 v9, v9
	v_exp_f32_e32 v8, v8
	v_add_f32_e32 v24, v107, v37
	v_mul_f32_e32 v24, 0xbfb8aa3b, v24
	v_mul_f32_e32 v22, v6, v22
	v_fma_f32 v5, -v7, v7, 1.0
	v_exp_f32_e32 v24, v24
	v_exp_f32_e32 v22, v22
	v_rcp_f32_e32 v4, v4
	v_max_f32_e32 v5, 0, v5
	v_sqrt_f32_e32 v5, v5
	v_add_f32_e32 v9, 1.0, v9
	v_fma_f32 v23, -v8, v8, 1.0
	v_rcp_f32_e32 v9, v9
	v_max_f32_e32 v23, 0, v23
	v_sqrt_f32_e32 v23, v23
	v_add_f32_e32 v24, 1.0, v24
	v_fma_f32 v25, -v22, v22, 1.0
	v_mul_f32_e32 v4, v31, v4
	v_rcp_f32_e32 v24, v24
	v_max_f32_e32 v25, 0, v25
	v_mul_f32_e32 v171, v7, v159
	v_sqrt_f32_e32 v25, v25
	v_fmac_f32_e32 v171, v4, v5
	v_mul_f32_e32 v9, v32, v9
	v_mul_f32_e32 v170, v8, v171
	v_mul_f32_e32 v188, v160, v7
	v_fmac_f32_e32 v170, v9, v23
	v_add_f32_e32 v5, v108, v18
	v_mul_f32_e32 v24, v33, v24
	v_mul_f32_e32 v189, v8, v188
	v_mul_f32_e32 v166, v22, v170
	v_mul_f32_e32 v5, 0xbfb8aa3b, v5
	v_mul_f32_e32 v190, v22, v189
	v_fmac_f32_e32 v166, v24, v25
	v_exp_f32_e32 v5, v5
	ds_bpermute_b32 v199, v95, v190
	ds_bpermute_b32 v201, v95, v166
	ds_bpermute_b32 v197, v95, v190 offset:64
	ds_bpermute_b32 v198, v95, v166 offset:64
	ds_bpermute_b32 v195, v95, v190 offset:128
	ds_bpermute_b32 v196, v95, v166 offset:128
	v_add_f32_e32 v9, v107, v14
	ds_bpermute_b32 v7, v95, v190 offset:192
	ds_bpermute_b32 v193, v95, v166 offset:192
	v_add_f32_e32 v5, 1.0, v5
	v_mul_f32_e32 v9, 0xbfb8aa3b, v9
	v_rcp_f32_e32 v5, v5
	v_exp_f32_e32 v9, v9
	s_waitcnt lgkmcnt(6)
	v_fmac_f32_e32 v201, 0, v199
	s_waitcnt lgkmcnt(4)
	v_fma_f32 v4, v201, v197, v198
	s_waitcnt lgkmcnt(2)
	v_fma_f32 v4, v4, v195, v196
	v_mul_f32_e32 v5, v6, v5
	s_waitcnt lgkmcnt(0)
	v_fmac_f32_e32 v193, v4, v7
	v_add_f32_e32 v4, 1.0, v9
	v_exp_f32_e32 v194, v5
	v_rcp_f32_e32 v4, v4
	v_add_f32_e32 v14, v107, v16
	v_mul_f32_e32 v14, 0xbfb8aa3b, v14
	v_fma_f32 v5, -v194, v194, 1.0
	v_mul_f32_e32 v4, v10, v4
	v_add_f32_e32 v10, v107, v15
	v_max_f32_e32 v5, 0, v5
	v_mul_f32_e32 v10, 0xbfb8aa3b, v10
	v_sqrt_f32_e32 v5, v5
	v_exp_f32_e32 v10, v10
	v_add_f32_e32 v9, v108, v19
	v_exp_f32_e32 v14, v14
	v_mul_f32_e32 v191, v4, v5
	v_add_f32_e32 v4, 1.0, v10
	v_rcp_f32_e32 v4, v4
	v_mul_f32_e32 v9, 0xbfb8aa3b, v9
	v_exp_f32_e32 v9, v9
	v_add_f32_e32 v10, v108, v20
	v_mul_f32_e32 v10, 0xbfb8aa3b, v10
	v_exp_f32_e32 v10, v10
	v_mul_f32_e32 v4, v11, v4
	v_add_f32_e32 v11, 1.0, v14
	v_add_f32_e32 v14, v108, v21
	v_mul_f32_e32 v14, 0xbfb8aa3b, v14
	v_add_f32_e32 v9, 1.0, v9
	v_exp_f32_e32 v14, v14
	v_rcp_f32_e32 v9, v9
	v_add_f32_e32 v10, 1.0, v10
	v_rcp_f32_e32 v10, v10
	v_add_f32_e32 v14, 1.0, v14
	v_mul_f32_e32 v9, v6, v9
	v_rcp_f32_e32 v14, v14
	v_exp_f32_e32 v9, v9
	v_mul_f32_e32 v10, v6, v10
	v_exp_f32_e32 v10, v10
	v_add_f32_e32 v16, v107, v17
	v_mul_f32_e32 v16, 0xbfb8aa3b, v16
	v_mul_f32_e32 v6, v6, v14
	v_fma_f32 v5, -v9, v9, 1.0
	v_rcp_f32_e32 v11, v11
	v_exp_f32_e32 v16, v16
	v_exp_f32_e32 v6, v6
	v_max_f32_e32 v5, 0, v5
	v_sqrt_f32_e32 v5, v5
	v_fma_f32 v15, -v10, v10, 1.0
	v_max_f32_e32 v15, 0, v15
	v_sqrt_f32_e32 v15, v15
	v_mul_f32_e32 v11, v12, v11
	v_add_f32_e32 v12, 1.0, v16
	v_fma_f32 v14, -v6, v6, 1.0
	v_rcp_f32_e32 v12, v12
	v_max_f32_e32 v14, 0, v14
	v_mul_f32_e32 v214, v9, v191
	v_sqrt_f32_e32 v14, v14
	v_fmac_f32_e32 v214, v4, v5
	v_mul_f32_e32 v213, v10, v214
	v_mul_f32_e32 v221, v194, v9
	v_fmac_f32_e32 v213, v11, v15
	v_mul_f32_e32 v12, v13, v12
	v_mul_f32_e32 v222, v10, v221
	v_mul_f32_e32 v203, v6, v213
	v_mul_f32_e32 v223, v6, v222
	v_fmac_f32_e32 v203, v12, v14
	ds_bpermute_b32 v6, v95, v223
	ds_bpermute_b32 v228, v95, v203
	ds_bpermute_b32 v73, v95, v69 offset:64
	ds_bpermute_b32 v89, v95, v135 offset:64
	ds_bpermute_b32 v71, v95, v69 offset:128
	ds_bpermute_b32 v72, v95, v135 offset:128
	ds_bpermute_b32 v96, v95, v69 offset:192
	ds_bpermute_b32 v58, v95, v135 offset:192
	ds_bpermute_b32 v183, v95, v169 offset:64
	ds_bpermute_b32 v184, v95, v153 offset:64
	ds_bpermute_b32 v181, v95, v169 offset:128
	ds_bpermute_b32 v182, v95, v153 offset:128
	ds_bpermute_b32 v42, v95, v169 offset:192
	ds_bpermute_b32 v26, v95, v153 offset:192
	ds_bpermute_b32 v217, v95, v211 offset:64
	ds_bpermute_b32 v218, v95, v179 offset:64
	ds_bpermute_b32 v215, v95, v211 offset:128
	ds_bpermute_b32 v216, v95, v179 offset:128
	ds_bpermute_b32 v3, v95, v211 offset:192
	ds_bpermute_b32 v2, v95, v179 offset:192
	ds_bpermute_b32 v226, v95, v223 offset:64
	ds_bpermute_b32 v227, v95, v203 offset:64
	ds_bpermute_b32 v224, v95, v223 offset:128
	ds_bpermute_b32 v225, v95, v203 offset:128
	ds_bpermute_b32 v5, v95, v223 offset:192
	ds_bpermute_b32 v4, v95, v203 offset:192
	v_mul_f32_e32 v8, v199, v197
	v_mul_f32_e32 v8, v8, v195
	v_mul_f32_e32 v229, v8, v7
	s_waitcnt lgkmcnt(14)
	v_fmac_f32_e32 v228, v193, v6
	v_mul_f32_e32 v230, v229, v6
	s_and_saveexec_b64 s[0:1], vcc
	s_cbranch_execz .LBB0_612
	s_waitcnt lgkmcnt(4)
	v_fma_f32 v7, v228, v226, v227
	s_waitcnt lgkmcnt(2)
	v_fma_f32 v7, v7, v224, v225
	v_mul_f32_e32 v6, v230, v226
	s_waitcnt lgkmcnt(0)
	v_fmac_f32_e32 v4, v7, v5
	v_fma_f32 v7, v219, v217, v218
	v_mul_f32_e32 v6, v6, v224
	v_fma_f32 v7, v7, v215, v216
	v_mul_f32_e32 v6, v6, v5
	v_mul_f32_e32 v5, v220, v217
	v_fmac_f32_e32 v2, v7, v3
	v_fma_f32 v7, v186, v183, v184
	v_mul_f32_e32 v5, v5, v215
	v_fma_f32 v7, v7, v181, v182
	v_fma_f32 v8, v94, v73, v89
	v_mul_f32_e32 v5, v5, v3
	v_mul_f32_e32 v3, v192, v183
	v_fmac_f32_e32 v26, v7, v42
	v_mul_f32_e32 v7, v54, v73
	v_fma_f32 v8, v8, v71, v72
	v_readlane_b32 s6, v251, 22
	v_mul_f32_e32 v3, v3, v181
	v_mul_f32_e32 v7, v7, v71
	v_fmac_f32_e32 v58, v8, v96
	v_or_b32_e32 v8, s6, v106
	v_mul_f32_e32 v3, v3, v42
	v_mul_f32_e32 v7, v7, v96
	v_lshl_add_u32 v8, v8, 2, 0
	ds_write2_b32 v8, v7, v3 offset1:16
	v_add_u32_e32 v3, 0x800, v8
	ds_write2_b32 v3, v58, v26 offset1:16
	ds_write2_b32 v8, v5, v6 offset0:32 offset1:48
	ds_write2_b32 v3, v2, v4 offset0:32 offset1:48
